# speedup vs baseline: 1.0532x; 1.0067x over previous
; template <int EPI> __device__ __forceinline__ void epi_res(const int tid_e, const GemmArgs& ga, int brow, int bcol, f32x4 (&acc)[2][2][4][2], char* epl) {
;   const int wr_e = tid_e >> 8, wc_e = (tid_e >> 6) & 3, fr_e = tid_e & 15, fq_e = (tid_e >> 4) & 3, lane_e = tid_e & 63;
;   char* sl = epl + (tid_e >> 6) * 4096;
;   const int rr = lane_e >> 3, rc = lane_e & 7;
;   const float* resf = (brow < TP) ? ga.res0 + (size_t)brow * DM : ga.res1 + (size_t)(brow - TP) * DM;
;   const int rl0 = wr_e * 64 + rr, cl0 = bcol + wc_e * 32 + rc * 4;
;   u32x2 rb[2][2][4]; f32x4 rf[2][4];
; #pragma unroll
;   for (int ai = 0; ai < 2; ++ai) {
;     if (EPI != 2) {
; #pragma unroll
;       for (int bj = 0; bj < 2; ++bj)
; #pragma unroll
;         for (int h = 0; h < 2; ++h)
; #pragma unroll
;           for (int i = 0; i < 4; ++i)
;             rb[bj][h][i] = *reinterpret_cast<const u32x2*>(ga.resb + (size_t)(brow + rl0 + ai * 128 + h * 32 + i * 8) * DM + cl0 + bj * 128);
;     }
; #pragma unroll
;     for (int bj = 0; bj < 2; ++bj) {
;       const int col = cl0 + bj * 128;
;       f32x4 scv = {1.f, 1.f, 1.f, 1.f};
;       if (EPI == 3) scv = *reinterpret_cast<const f32x4*>(ga.scale + col);
;       if (EPI == 2) {
; #pragma unroll
;         for (int h = 0; h < 2; ++h)
; #pragma unroll
;           for (int i = 0; i < 4; ++i)
;             rf[h][i] = *reinterpret_cast<const f32x4*>(resf + (size_t)(rl0 + ai * 128 + h * 32 + i * 8) * DM + col);
;       }
; #pragma unroll
;       for (int h = 0; h < 2; ++h) {
; #pragma unroll
;         for (int mm = 0; mm < 2; ++mm) {
;           const int lrow = mm * 16 + fr_e;
; #pragma unroll
;           for (int n = 0; n < 2; ++n)
;             *reinterpret_cast<f32x4*>(sl + lrow * 128 + (((n * 4 + fq_e) ^ ((lrow >> 1) & 7)) * 16)) = acc[ai][bj][h * 2 + mm][n];
;         }
;         f32x4 v[4];
; #pragma unroll
;         for (int i = 0; i < 4; ++i) { const int lrow = i * 8 + rr;
;           v[i] = *reinterpret_cast<const f32x4*>(sl + lrow * 128 + ((rc ^ ((lrow >> 1) & 7)) * 16)); }
; #pragma unroll
;         for (int i = 0; i < 4; ++i) {
;           const int row = brow + rl0 + ai * 128 + h * 32 + i * 8;
;           f32x4 x = v[i];
;           if (EPI == 3) x = x * scv;
;           if (EPI == 2) x = x + rf[h][i];
.LBB0_416:
	s_and_b64 vcc, exec, s[6:7]
	s_cbranch_vccz .LBB0_483
	s_cmp_eq_u32 s53, 4
	s_mov_b64 s[70:71], -1
	s_cbranch_scc0 .LBB0_483
	v_bfe_u32 v229, v226, 3, 3
	v_ashrrev_i32_e32 v98, 2, v226
	v_and_b32_e32 v132, 7, v226
	v_and_or_b32 v99, v98, s33, v229
	v_lshlrev_b32_e32 v98, 5, v227
	v_and_b32_e32 v98, 0x60, v98
	v_lshlrev_b32_e32 v133, 2, v132
	v_or3_b32 v98, v98, v133, s16
	s_add_i32 s6, 0, 0x20000
	v_add_u32_e32 v144, s3, v99
	v_ashrrev_i32_e32 v99, 31, v98
	v_lshlrev_b32_e32 v133, 7, v226
	v_lshl_add_u32 v202, v227, 12, s6
	v_and_b32_e32 v133, 0x780, v133
	v_cmp_eq_u32_e32 vcc, 0, v132
	v_lshlrev_b64 v[182:183], 1, v[98:99]
	v_or_b32_e32 v132, 32, v144
	v_ashrrev_i32_e32 v145, 31, v144
	v_add_u32_e32 v203, v202, v133
	v_lshl_add_u64 v[146:147], s[94:95], 0, v[182:183]
	v_ashrrev_i32_e32 v133, 31, v132
	v_lshlrev_b64 v[148:149], 12, v[144:145]
	v_lshlrev_b64 v[174:175], 12, v[132:133]
	v_lshl_add_u64 v[132:133], v[146:147], 0, v[148:149]
	global_load_dwordx2 v[234:235], v[132:133], off
	v_or_b32_e32 v134, 8, v144
	v_or_b32_e32 v136, 16, v144
	v_or_b32_e32 v138, 24, v144
	v_or_b32_e32 v142, 40, v144
	v_or_b32_e32 v152, 48, v144
	v_or_b32_e32 v154, 56, v144
	v_ashrrev_i32_e32 v135, 31, v134
	v_ashrrev_i32_e32 v137, 31, v136
	v_ashrrev_i32_e32 v139, 31, v138
	v_ashrrev_i32_e32 v143, 31, v142
	v_ashrrev_i32_e32 v153, 31, v152
	v_ashrrev_i32_e32 v155, 31, v154
	v_lshlrev_b64 v[192:193], 12, v[134:135]
	v_lshlrev_b64 v[190:191], 12, v[136:137]
	v_lshlrev_b64 v[186:187], 12, v[138:139]
	v_lshlrev_b64 v[178:179], 12, v[142:143]
	v_lshlrev_b64 v[172:173], 12, v[152:153]
	v_lshlrev_b64 v[168:169], 12, v[154:155]
	v_lshl_add_u64 v[134:135], v[146:147], 0, v[192:193]
	v_lshl_add_u64 v[136:137], v[146:147], 0, v[190:191]
	v_lshl_add_u64 v[138:139], v[146:147], 0, v[186:187]
	v_lshl_add_u64 v[140:141], v[146:147], 0, v[174:175]
	v_lshl_add_u64 v[142:143], v[146:147], 0, v[178:179]
	v_lshl_add_u64 v[152:153], v[146:147], 0, v[172:173]
	v_lshl_add_u64 v[198:199], v[146:147], 0, v[168:169]
	global_load_dwordx2 v[196:197], v[134:135], off
	global_load_dwordx2 v[194:195], v[136:137], off
	global_load_dwordx2 v[188:189], v[138:139], off
	global_load_dwordx2 v[184:185], v[140:141], off
	global_load_dwordx2 v[180:181], v[142:143], off
	global_load_dwordx2 v[176:177], v[152:153], off
	global_load_dwordx2 v[170:171], v[198:199], off
	global_load_dwordx2 v[166:167], v[132:133], off offset:256
	global_load_dwordx2 v[164:165], v[134:135], off offset:256
	global_load_dwordx2 v[162:163], v[136:137], off offset:256
	global_load_dwordx2 v[160:161], v[138:139], off offset:256
	global_load_dwordx2 v[158:159], v[140:141], off offset:256
	global_load_dwordx2 v[156:157], v[142:143], off offset:256
	global_load_dwordx2 v[154:155], v[152:153], off offset:256
	s_nop 0
	global_load_dwordx2 v[152:153], v[198:199], off offset:256
	v_lshrrev_b32_e32 v96, 4, v226
	v_bfe_u32 v230, v226, 1, 3
	v_lshrrev_b32_e32 v228, 3, v226
	v_bitop3_b32 v96, v96, v230, 3 bitop3:0x6c
	v_bfe_u32 v200, v226, 4, 2
	v_lshlrev_b32_e32 v96, 4, v96
	v_bfe_u32 v132, v228, 1, 2
	v_add_u32_e32 v201, v203, v96
	v_bitop3_b32 v96, v200, v230, 4 bitop3:0x36
	v_xor_b32_e32 v132, v132, v226
	v_lshlrev_b32_e32 v96, 4, v96
	v_lshlrev_b32_e32 v132, 4, v132
	v_add_u32_e32 v203, v203, v96
	v_lshl_add_u32 v96, v229, 7, v202
	v_and_b32_e32 v132, 0x70, v132
	v_add_u32_e32 v228, v96, v132
	v_or_b32_e32 v96, 8, v229
	v_lshl_add_u32 v132, v96, 7, v202
	v_lshrrev_b32_e32 v96, 1, v96
	v_xor_b32_e32 v96, v96, v226
	v_lshlrev_b32_e32 v96, 4, v96
	ds_write_b128 v201, v[128:131]
	ds_write_b128 v203, v[124:127]
	ds_write_b128 v201, v[120:123] offset:2048
	ds_write_b128 v203, v[116:119] offset:2048
	v_and_b32_e32 v96, 0x70, v96
	ds_read_b128 v[230:233], v228
	v_add_u32_e32 v199, v132, v96
	v_or_b32_e32 v96, 24, v229
	v_lshl_add_u32 v132, v96, 7, v202
	v_lshrrev_b32_e32 v96, 1, v96
	v_xor_b32_e32 v96, v96, v226
	v_lshlrev_b32_e32 v96, 4, v96
	v_and_b32_e32 v96, 0x70, v96
	v_add_u32_e32 v202, v132, v96
	ds_read_b128 v[140:143], v199
	ds_read_b128 v[136:139], v228 offset:2048
	ds_read_b128 v[132:135], v202
	v_lshl_add_u64 v[144:145], v[144:145], 2, s[56:57]
	s_waitcnt vmcnt(15)
	v_and_b32_e32 v198, 0xffff0000, v234
	v_lshlrev_b32_e32 v96, 16, v234
	s_waitcnt lgkmcnt(3)
	v_add_f32_e32 v198, v231, v198
	v_add_f32_e32 v96, v230, v96
	v_lshlrev_b32_e32 v200, 16, v235
	v_cvt_pk_bf16_f32 v230, v96, v198
	v_mul_f32_e32 v198, v198, v198
	v_add_f32_e32 v200, v232, v200
	v_and_b32_e32 v229, 0xffff0000, v235
	v_fmac_f32_e32 v198, v96, v96
	v_add_f32_e32 v229, v233, v229
	v_cvt_pk_bf16_f32 v231, v200, v229
	v_fmac_f32_e32 v198, v200, v200
	v_and_b32_e32 v200, 64, v212
	v_xor_b32_e32 v96, 1, v212
	v_add_u32_e32 v200, 64, v200
	v_cmp_lt_i32_e64 s[6:7], v96, v200
	v_fmac_f32_e32 v198, v229, v229
	v_lshl_add_u64 v[232:233], s[96:97], 0, v[148:149]
	v_cndmask_b32_e64 v96, v212, v96, s[6:7]
	v_lshlrev_b32_e32 v96, 2, v96
	s_nop 1
	v_mov_b32_dpp v229, v198 quad_perm:[1,0,3,2] row_mask:0xf bank_mask:0xf
	v_lshl_add_u64 v[182:183], v[232:233], 0, v[182:183]
	global_store_dwordx2 v[182:183], v[230:231], off
	s_waitcnt lgkmcnt(0)
	v_add_f32_e32 v229, v198, v229
	v_xor_b32_e32 v198, 2, v212
	v_cmp_lt_i32_e64 s[6:7], v198, v200
	s_nop 1
	v_cndmask_b32_e64 v198, v212, v198, s[6:7]
	v_lshlrev_b32_e32 v198, 2, v198
	s_nop 1
	v_mov_b32_dpp v230, v229 quad_perm:[2,3,0,1] row_mask:0xf bank_mask:0xf
	s_waitcnt lgkmcnt(0)
	v_add_f32_e32 v229, v229, v230
	v_xor_b32_e32 v230, 4, v212
	v_cmp_lt_i32_e64 s[6:7], v230, v200
	s_nop 1
	v_cndmask_b32_e64 v200, v212, v230, s[6:7]
	v_lshlrev_b32_e32 v200, 2, v200
	s_nop 1
	v_mov_b32_dpp v230, v229 row_half_mirror row_mask:0xf bank_mask:0xf
	s_and_saveexec_b64 s[6:7], vcc
	s_cbranch_execz .LBB0_420
	s_waitcnt lgkmcnt(0)
	v_add_f32_e32 v229, v229, v230
	global_atomic_add_f32 v[144:145], v229, off
; __device__ __forceinline__ float bflo(unsigned w) { return __uint_as_float(w << 16); }
; __device__ __forceinline__ float bfhi(unsigned w) { return __uint_as_float(w & 0xffff0000u); }
; template <int EPI> __device__ __forceinline__ void epi_res(const int tid_e, const GemmArgs& ga, int brow, int bcol, f32x4 (&acc)[2][2][4][2], char* epl) {
;     ...
;       for (int h = 0; h < 2; ++h) {
; #pragma unroll
;         for (int mm = 0; mm < 2; ++mm) {
;           const int lrow = mm * 16 + fr_e;
; #pragma unroll
;           for (int n = 0; n < 2; ++n)
;             *reinterpret_cast<f32x4*>(sl + lrow * 128 + (((n * 4 + fq_e) ^ ((lrow >> 1) & 7)) * 16)) = acc[ai][bj][h * 2 + mm][n];
;         }
;         f32x4 v[4];
; #pragma unroll
;         for (int i = 0; i < 4; ++i) { const int lrow = i * 8 + rr;
;           v[i] = *reinterpret_cast<const f32x4*>(sl + lrow * 128 + ((rc ^ ((lrow >> 1) & 7)) * 16)); }
; #pragma unroll
;         for (int i = 0; i < 4; ++i) {
;           const int row = brow + rl0 + ai * 128 + h * 32 + i * 8;
;           f32x4 x = v[i];
;           if (EPI == 3) x = x * scv;
;           if (EPI == 2) x = x + rf[h][i];
;           else { const u32x2 r = rb[bj][h][i]; x[0] += bflo(r[0]); x[1] += bfhi(r[0]); x[2] += bflo(r[1]); x[3] += bfhi(r[1]); }
;           if (EPI == 5) *reinterpret_cast<f32x4*>(ga.outf + (size_t)row * DM + col) = x;
;           else {
;             u32x2 w = {cvtpk(x[0], x[1]), cvtpk(x[2], x[3])};
;             *reinterpret_cast<u32x2*>(ga.Cb + (size_t)row * DM + col) = w;
;             float ss = x[0] * x[0] + x[1] * x[1] + x[2] * x[2] + x[3] * x[3];
;             ss += __shfl_xor(ss, 1); ss += __shfl_xor(ss, 2); ss += __shfl_xor(ss, 4);
;             if (rc == 0) atomicAdd(ga.rss_out + row, ss);
;           }
.LBB0_420:
	s_or_b64 exec, exec, s[6:7]
	s_waitcnt vmcnt(15)
	v_lshlrev_b32_e32 v229, 16, v196
	v_and_b32_e32 v196, 0xffff0000, v196
	v_add_f32_e32 v141, v141, v196
	v_lshlrev_b32_e32 v196, 16, v197
	v_add_f32_e32 v196, v142, v196
	v_and_b32_e32 v142, 0xffff0000, v197
	v_add_f32_e32 v140, v140, v229
	v_add_f32_e32 v143, v143, v142
	v_mul_f32_e32 v142, v141, v141
	v_fmac_f32_e32 v142, v140, v140
	v_fmac_f32_e32 v142, v196, v196
	v_fmac_f32_e32 v142, v143, v143
	s_nop 1
	v_mov_b32_dpp v197, v142 quad_perm:[1,0,3,2] row_mask:0xf bank_mask:0xf
	v_lshl_add_u64 v[192:193], s[96:97], 0, v[192:193]
	v_lshl_add_u64 v[192:193], v[98:99], 1, v[192:193]
	v_cvt_pk_bf16_f32 v143, v196, v143
	s_waitcnt lgkmcnt(0)
	v_add_f32_e32 v197, v142, v197
	s_nop 1
	v_mov_b32_dpp v229, v197 quad_perm:[2,3,0,1] row_mask:0xf bank_mask:0xf
	v_cvt_pk_bf16_f32 v142, v140, v141
	global_store_dwordx2 v[192:193], v[142:143], off
	s_waitcnt lgkmcnt(0)
	v_add_f32_e32 v140, v197, v229
	s_nop 1
	v_mov_b32_dpp v141, v140 row_half_mirror row_mask:0xf bank_mask:0xf
	s_and_saveexec_b64 s[6:7], vcc
	s_cbranch_execz .LBB0_422
	s_waitcnt lgkmcnt(0)
	v_add_f32_e32 v140, v140, v141
	global_atomic_add_f32 v[144:145], v140, off offset:32
.LBB0_422:
	s_or_b64 exec, exec, s[6:7]
	s_waitcnt vmcnt(15)
	v_lshlrev_b32_e32 v140, 16, v194
	v_add_f32_e32 v136, v136, v140
	v_and_b32_e32 v140, 0xffff0000, v194
	v_add_f32_e32 v137, v137, v140
	v_lshlrev_b32_e32 v140, 16, v195
	v_add_f32_e32 v140, v138, v140
	v_and_b32_e32 v138, 0xffff0000, v195
	v_add_f32_e32 v139, v139, v138
	v_mul_f32_e32 v138, v137, v137
	v_fmac_f32_e32 v138, v136, v136
	v_fmac_f32_e32 v138, v140, v140
	v_fmac_f32_e32 v138, v139, v139
	s_waitcnt lgkmcnt(0)
	s_nop 1
	v_mov_b32_dpp v141, v138 quad_perm:[1,0,3,2] row_mask:0xf bank_mask:0xf
	v_cvt_pk_bf16_f32 v139, v140, v139
	s_waitcnt lgkmcnt(0)
	v_add_f32_e32 v141, v138, v141
	s_nop 1
	v_mov_b32_dpp v142, v141 quad_perm:[2,3,0,1] row_mask:0xf bank_mask:0xf
	v_cvt_pk_bf16_f32 v138, v136, v137
	s_waitcnt lgkmcnt(0)
	v_add_f32_e32 v136, v141, v142
	s_nop 1
	v_mov_b32_dpp v137, v136 row_half_mirror row_mask:0xf bank_mask:0xf
	v_lshl_add_u64 v[140:141], s[96:97], 0, v[190:191]
	v_lshl_add_u64 v[190:191], v[98:99], 1, v[140:141]
	global_store_dwordx2 v[190:191], v[138:139], off
	s_and_saveexec_b64 s[6:7], vcc
	s_cbranch_execz .LBB0_424
	s_waitcnt lgkmcnt(0)
	v_add_f32_e32 v136, v136, v137
	global_atomic_add_f32 v[144:145], v136, off offset:64
.LBB0_424:
	s_or_b64 exec, exec, s[6:7]
	s_waitcnt vmcnt(15)
	v_lshlrev_b32_e32 v136, 16, v188
	v_add_f32_e32 v132, v132, v136
	v_and_b32_e32 v136, 0xffff0000, v188
	v_add_f32_e32 v133, v133, v136
	v_lshlrev_b32_e32 v136, 16, v189
	v_add_f32_e32 v136, v134, v136
	v_and_b32_e32 v134, 0xffff0000, v189
	v_add_f32_e32 v135, v135, v134
	v_mul_f32_e32 v134, v133, v133
	v_fmac_f32_e32 v134, v132, v132
	v_fmac_f32_e32 v134, v136, v136
	v_fmac_f32_e32 v134, v135, v135
	s_waitcnt lgkmcnt(0)
	s_nop 1
	v_mov_b32_dpp v137, v134 quad_perm:[1,0,3,2] row_mask:0xf bank_mask:0xf
	v_cvt_pk_bf16_f32 v135, v136, v135
	s_waitcnt lgkmcnt(0)
	v_add_f32_e32 v137, v134, v137
	s_nop 1
	v_mov_b32_dpp v138, v137 quad_perm:[2,3,0,1] row_mask:0xf bank_mask:0xf
	v_cvt_pk_bf16_f32 v134, v132, v133
	s_waitcnt lgkmcnt(0)
	v_add_f32_e32 v132, v137, v138
	s_nop 1
	v_mov_b32_dpp v133, v132 row_half_mirror row_mask:0xf bank_mask:0xf
	v_lshl_add_u64 v[136:137], s[96:97], 0, v[186:187]
	v_lshl_add_u64 v[186:187], v[98:99], 1, v[136:137]
	global_store_dwordx2 v[186:187], v[134:135], off
	s_and_saveexec_b64 s[6:7], vcc
	s_cbranch_execz .LBB0_426
	s_waitcnt lgkmcnt(0)
	v_add_f32_e32 v132, v132, v133
	global_atomic_add_f32 v[144:145], v132, off offset:96
.LBB0_426:
	s_or_b64 exec, exec, s[6:7]
	ds_write_b128 v201, v[112:115]
	ds_write_b128 v203, v[108:111]
	s_waitcnt lgkmcnt(2)
	ds_read_b128 v[132:135], v228
	s_waitcnt vmcnt(15)
	v_lshlrev_b32_e32 v140, 16, v184
	ds_write_b128 v201, v[104:107] offset:2048
	ds_write_b128 v203, v[100:103] offset:2048
	ds_read_b128 v[136:139], v228 offset:2048
	v_lshl_add_u64 v[174:175], s[96:97], 0, v[174:175]
	s_waitcnt lgkmcnt(3)
	v_add_f32_e32 v188, v132, v140
	v_and_b32_e32 v132, 0xffff0000, v184
	v_add_f32_e32 v184, v133, v132
	v_lshlrev_b32_e32 v132, 16, v185
	v_add_f32_e32 v189, v134, v132
	v_and_b32_e32 v132, 0xffff0000, v185
	v_add_f32_e32 v194, v135, v132
	v_mul_f32_e32 v132, v184, v184
	v_fmac_f32_e32 v132, v188, v188
	v_fmac_f32_e32 v132, v189, v189
	v_fmac_f32_e32 v132, v194, v194
	s_nop 1
	v_mov_b32_dpp v133, v132 quad_perm:[1,0,3,2] row_mask:0xf bank_mask:0xf
	v_cvt_pk_bf16_f32 v188, v188, v184
	v_lshl_add_u64 v[174:175], v[98:99], 1, v[174:175]
	v_cvt_pk_bf16_f32 v189, v189, v194
	s_waitcnt lgkmcnt(0)
	v_add_f32_e32 v185, v132, v133
	s_nop 1
	v_mov_b32_dpp v195, v185 quad_perm:[2,3,0,1] row_mask:0xf bank_mask:0xf
	ds_read_b128 v[140:143], v199
	ds_read_b128 v[132:135], v202
	global_store_dwordx2 v[174:175], v[188:189], off
	s_waitcnt lgkmcnt(2)
	v_add_f32_e32 v184, v185, v195
	s_nop 1
	v_mov_b32_dpp v185, v184 row_half_mirror row_mask:0xf bank_mask:0xf
	s_and_saveexec_b64 s[6:7], vcc
	s_cbranch_execz .LBB0_428
	s_waitcnt lgkmcnt(0)
	v_add_f32_e32 v184, v184, v185
	global_atomic_add_f32 v[144:145], v184, off offset:128
; __device__ __forceinline__ float bflo(unsigned w) { return __uint_as_float(w << 16); }
; __device__ __forceinline__ float bfhi(unsigned w) { return __uint_as_float(w & 0xffff0000u); }
; template <int EPI> __device__ __forceinline__ void epi_res(const int tid_e, const GemmArgs& ga, int brow, int bcol, f32x4 (&acc)[2][2][4][2], char* epl) {
;     ...
;       for (int h = 0; h < 2; ++h) {
; #pragma unroll
;         for (int mm = 0; mm < 2; ++mm) {
;           const int lrow = mm * 16 + fr_e;
; #pragma unroll
;           for (int n = 0; n < 2; ++n)
;             *reinterpret_cast<f32x4*>(sl + lrow * 128 + (((n * 4 + fq_e) ^ ((lrow >> 1) & 7)) * 16)) = acc[ai][bj][h * 2 + mm][n];
;         }
;         f32x4 v[4];
; #pragma unroll
;         for (int i = 0; i < 4; ++i) { const int lrow = i * 8 + rr;
;           v[i] = *reinterpret_cast<const f32x4*>(sl + lrow * 128 + ((rc ^ ((lrow >> 1) & 7)) * 16)); }
; #pragma unroll
;         for (int i = 0; i < 4; ++i) {
;           const int row = brow + rl0 + ai * 128 + h * 32 + i * 8;
;           f32x4 x = v[i];
;           if (EPI == 3) x = x * scv;
;           if (EPI == 2) x = x + rf[h][i];
;           else { const u32x2 r = rb[bj][h][i]; x[0] += bflo(r[0]); x[1] += bfhi(r[0]); x[2] += bflo(r[1]); x[3] += bfhi(r[1]); }
;           if (EPI == 5) *reinterpret_cast<f32x4*>(ga.outf + (size_t)row * DM + col) = x;
;           else {
;             u32x2 w = {cvtpk(x[0], x[1]), cvtpk(x[2], x[3])};
;             *reinterpret_cast<u32x2*>(ga.Cb + (size_t)row * DM + col) = w;
;             float ss = x[0] * x[0] + x[1] * x[1] + x[2] * x[2] + x[3] * x[3];
;             ss += __shfl_xor(ss, 1); ss += __shfl_xor(ss, 2); ss += __shfl_xor(ss, 4);
;             if (rc == 0) atomicAdd(ga.rss_out + row, ss);
;           }
.LBB0_428:
	s_or_b64 exec, exec, s[6:7]
	s_waitcnt vmcnt(15)
	v_lshlrev_b32_e32 v184, 16, v180
	v_and_b32_e32 v180, 0xffff0000, v180
	s_waitcnt lgkmcnt(1)
	v_add_f32_e32 v141, v141, v180
	v_lshlrev_b32_e32 v180, 16, v181
	v_add_f32_e32 v180, v142, v180
	v_and_b32_e32 v142, 0xffff0000, v181
	v_add_f32_e32 v140, v140, v184
	v_add_f32_e32 v143, v143, v142
	v_mul_f32_e32 v142, v141, v141
	v_fmac_f32_e32 v142, v140, v140
	v_fmac_f32_e32 v142, v180, v180
	v_fmac_f32_e32 v142, v143, v143
	s_nop 1
	v_mov_b32_dpp v181, v142 quad_perm:[1,0,3,2] row_mask:0xf bank_mask:0xf
	v_lshl_add_u64 v[178:179], s[96:97], 0, v[178:179]
	v_lshl_add_u64 v[178:179], v[98:99], 1, v[178:179]
	v_cvt_pk_bf16_f32 v143, v180, v143
	s_waitcnt lgkmcnt(0)
	v_add_f32_e32 v181, v142, v181
	s_nop 1
	v_mov_b32_dpp v184, v181 quad_perm:[2,3,0,1] row_mask:0xf bank_mask:0xf
	v_cvt_pk_bf16_f32 v142, v140, v141
	global_store_dwordx2 v[178:179], v[142:143], off
	s_waitcnt lgkmcnt(0)
	v_add_f32_e32 v140, v181, v184
	s_nop 1
	v_mov_b32_dpp v141, v140 row_half_mirror row_mask:0xf bank_mask:0xf
	s_and_saveexec_b64 s[6:7], vcc
	s_cbranch_execz .LBB0_430
	s_waitcnt lgkmcnt(0)
	v_add_f32_e32 v140, v140, v141
	global_atomic_add_f32 v[144:145], v140, off offset:160
.LBB0_430:
	s_or_b64 exec, exec, s[6:7]
	s_waitcnt vmcnt(15)
	v_lshlrev_b32_e32 v140, 16, v176
	v_add_f32_e32 v136, v136, v140
	v_and_b32_e32 v140, 0xffff0000, v176
	v_add_f32_e32 v137, v137, v140
	v_lshlrev_b32_e32 v140, 16, v177
	v_add_f32_e32 v140, v138, v140
	v_and_b32_e32 v138, 0xffff0000, v177
	v_add_f32_e32 v139, v139, v138
	v_mul_f32_e32 v138, v137, v137
	v_fmac_f32_e32 v138, v136, v136
	v_fmac_f32_e32 v138, v140, v140
	v_fmac_f32_e32 v138, v139, v139
	s_waitcnt lgkmcnt(0)
	s_nop 1
	v_mov_b32_dpp v141, v138 quad_perm:[1,0,3,2] row_mask:0xf bank_mask:0xf
	v_cvt_pk_bf16_f32 v139, v140, v139
	s_waitcnt lgkmcnt(0)
	v_add_f32_e32 v141, v138, v141
	s_nop 1
	v_mov_b32_dpp v142, v141 quad_perm:[2,3,0,1] row_mask:0xf bank_mask:0xf
	v_cvt_pk_bf16_f32 v138, v136, v137
	s_waitcnt lgkmcnt(0)
	v_add_f32_e32 v136, v141, v142
	s_nop 1
	v_mov_b32_dpp v137, v136 row_half_mirror row_mask:0xf bank_mask:0xf
	v_lshl_add_u64 v[140:141], s[96:97], 0, v[172:173]
	v_lshl_add_u64 v[172:173], v[98:99], 1, v[140:141]
	global_store_dwordx2 v[172:173], v[138:139], off
	s_and_saveexec_b64 s[6:7], vcc
	s_cbranch_execz .LBB0_432
	s_waitcnt lgkmcnt(0)
	v_add_f32_e32 v136, v136, v137
	global_atomic_add_f32 v[144:145], v136, off offset:192
.LBB0_432:
	s_or_b64 exec, exec, s[6:7]
	s_waitcnt vmcnt(15)
	v_lshlrev_b32_e32 v136, 16, v170
	v_add_f32_e32 v132, v132, v136
	v_and_b32_e32 v136, 0xffff0000, v170
	v_add_f32_e32 v133, v133, v136
	v_lshlrev_b32_e32 v136, 16, v171
	v_add_f32_e32 v136, v134, v136
	v_and_b32_e32 v134, 0xffff0000, v171
	v_add_f32_e32 v135, v135, v134
	v_mul_f32_e32 v134, v133, v133
	v_fmac_f32_e32 v134, v132, v132
	v_fmac_f32_e32 v134, v136, v136
	v_fmac_f32_e32 v134, v135, v135
	s_waitcnt lgkmcnt(0)
	s_nop 1
	v_mov_b32_dpp v137, v134 quad_perm:[1,0,3,2] row_mask:0xf bank_mask:0xf
	v_cvt_pk_bf16_f32 v135, v136, v135
	s_waitcnt lgkmcnt(0)
	v_add_f32_e32 v137, v134, v137
	s_nop 1
	v_mov_b32_dpp v138, v137 quad_perm:[2,3,0,1] row_mask:0xf bank_mask:0xf
	v_cvt_pk_bf16_f32 v134, v132, v133
	s_waitcnt lgkmcnt(0)
	v_add_f32_e32 v132, v137, v138
	s_nop 1
	v_mov_b32_dpp v133, v132 row_half_mirror row_mask:0xf bank_mask:0xf
	v_lshl_add_u64 v[136:137], s[96:97], 0, v[168:169]
	v_lshl_add_u64 v[168:169], v[98:99], 1, v[136:137]
	global_store_dwordx2 v[168:169], v[134:135], off
	s_and_saveexec_b64 s[6:7], vcc
	s_cbranch_execz .LBB0_434
	s_waitcnt lgkmcnt(0)
	v_add_f32_e32 v132, v132, v133
	global_atomic_add_f32 v[144:145], v132, off offset:224
.LBB0_434:
	s_or_b64 exec, exec, s[6:7]
	ds_write_b128 v201, v[92:95]
	ds_write_b128 v203, v[88:91]
	s_waitcnt lgkmcnt(2)
	ds_read_b128 v[132:135], v228
	s_waitcnt vmcnt(15)
	v_lshlrev_b32_e32 v140, 16, v166
	ds_write_b128 v201, v[84:87] offset:2048
	ds_write_b128 v203, v[80:83] offset:2048
	ds_read_b128 v[136:139], v228 offset:2048
	s_waitcnt lgkmcnt(3)
	v_add_f32_e32 v170, v132, v140
	v_and_b32_e32 v132, 0xffff0000, v166
	v_add_f32_e32 v171, v133, v132
	v_lshlrev_b32_e32 v132, 16, v167
	v_add_f32_e32 v176, v134, v132
	v_and_b32_e32 v132, 0xffff0000, v167
	v_add_f32_e32 v177, v135, v132
	v_mul_f32_e32 v132, v171, v171
	v_fmac_f32_e32 v132, v170, v170
	v_fmac_f32_e32 v132, v176, v176
	v_fmac_f32_e32 v132, v177, v177
	s_nop 1
	v_mov_b32_dpp v133, v132 quad_perm:[1,0,3,2] row_mask:0xf bank_mask:0xf
	v_cvt_pk_bf16_f32 v170, v170, v171
	v_cvt_pk_bf16_f32 v171, v176, v177
	s_waitcnt lgkmcnt(0)
	v_add_f32_e32 v166, v132, v133
	s_nop 1
	v_mov_b32_dpp v167, v166 quad_perm:[2,3,0,1] row_mask:0xf bank_mask:0xf
	ds_read_b128 v[140:143], v199
	ds_read_b128 v[132:135], v202
	global_store_dwordx2 v[182:183], v[170:171], off offset:256
	s_waitcnt lgkmcnt(2)
	v_add_f32_e32 v166, v166, v167
	s_nop 1
	v_mov_b32_dpp v167, v166 row_half_mirror row_mask:0xf bank_mask:0xf
	s_and_saveexec_b64 s[6:7], vcc
	s_cbranch_execz .LBB0_436
	s_waitcnt lgkmcnt(0)
	v_add_f32_e32 v166, v166, v167
	global_atomic_add_f32 v[144:145], v166, off
; __device__ __forceinline__ float bflo(unsigned w) { return __uint_as_float(w << 16); }
; __device__ __forceinline__ float bfhi(unsigned w) { return __uint_as_float(w & 0xffff0000u); }
; template <int EPI> __device__ __forceinline__ void epi_res(const int tid_e, const GemmArgs& ga, int brow, int bcol, f32x4 (&acc)[2][2][4][2], char* epl) {
;     ...
;       for (int h = 0; h < 2; ++h) {
; #pragma unroll
;         for (int mm = 0; mm < 2; ++mm) {
;           const int lrow = mm * 16 + fr_e;
; #pragma unroll
;           for (int n = 0; n < 2; ++n)
;             *reinterpret_cast<f32x4*>(sl + lrow * 128 + (((n * 4 + fq_e) ^ ((lrow >> 1) & 7)) * 16)) = acc[ai][bj][h * 2 + mm][n];
;         }
;         f32x4 v[4];
; #pragma unroll
;         for (int i = 0; i < 4; ++i) { const int lrow = i * 8 + rr;
;           v[i] = *reinterpret_cast<const f32x4*>(sl + lrow * 128 + ((rc ^ ((lrow >> 1) & 7)) * 16)); }
; #pragma unroll
;         for (int i = 0; i < 4; ++i) {
;           const int row = brow + rl0 + ai * 128 + h * 32 + i * 8;
;           f32x4 x = v[i];
;           if (EPI == 3) x = x * scv;
;           if (EPI == 2) x = x + rf[h][i];
;           else { const u32x2 r = rb[bj][h][i]; x[0] += bflo(r[0]); x[1] += bfhi(r[0]); x[2] += bflo(r[1]); x[3] += bfhi(r[1]); }
;           if (EPI == 5) *reinterpret_cast<f32x4*>(ga.outf + (size_t)row * DM + col) = x;
;           else {
;             u32x2 w = {cvtpk(x[0], x[1]), cvtpk(x[2], x[3])};
;             *reinterpret_cast<u32x2*>(ga.Cb + (size_t)row * DM + col) = w;
;             float ss = x[0] * x[0] + x[1] * x[1] + x[2] * x[2] + x[3] * x[3];
;             ss += __shfl_xor(ss, 1); ss += __shfl_xor(ss, 2); ss += __shfl_xor(ss, 4);
;             if (rc == 0) atomicAdd(ga.rss_out + row, ss);
;           }
.LBB0_436:
	s_or_b64 exec, exec, s[6:7]
	s_waitcnt vmcnt(15)
	v_lshlrev_b32_e32 v166, 16, v164
	s_waitcnt lgkmcnt(1)
	v_add_f32_e32 v166, v140, v166
	v_and_b32_e32 v140, 0xffff0000, v164
	v_add_f32_e32 v164, v141, v140
	v_lshlrev_b32_e32 v140, 16, v165
	s_waitcnt lgkmcnt(0)
	v_add_f32_e32 v167, v142, v140
	v_and_b32_e32 v140, 0xffff0000, v165
	v_add_f32_e32 v143, v143, v140
	v_mul_f32_e32 v140, v164, v164
	v_fmac_f32_e32 v140, v166, v166
	v_fmac_f32_e32 v140, v167, v167
	v_fmac_f32_e32 v140, v143, v143
	s_nop 1
	v_mov_b32_dpp v141, v140 quad_perm:[1,0,3,2] row_mask:0xf bank_mask:0xf
	v_cvt_pk_bf16_f32 v142, v166, v164
	v_cvt_pk_bf16_f32 v143, v167, v143
	global_store_dwordx2 v[192:193], v[142:143], off offset:256
	s_waitcnt lgkmcnt(0)
	v_add_f32_e32 v140, v140, v141
	s_nop 1
	v_mov_b32_dpp v141, v140 quad_perm:[2,3,0,1] row_mask:0xf bank_mask:0xf
	s_waitcnt lgkmcnt(0)
	v_add_f32_e32 v140, v140, v141
	s_nop 1
	v_mov_b32_dpp v141, v140 row_half_mirror row_mask:0xf bank_mask:0xf
	s_and_saveexec_b64 s[6:7], vcc
	s_cbranch_execz .LBB0_438
	s_waitcnt lgkmcnt(0)
	v_add_f32_e32 v140, v140, v141
	global_atomic_add_f32 v[144:145], v140, off offset:32
.LBB0_438:
	s_or_b64 exec, exec, s[6:7]
	s_waitcnt vmcnt(15)
	v_lshlrev_b32_e32 v140, 16, v162
	v_add_f32_e32 v140, v136, v140
	v_and_b32_e32 v136, 0xffff0000, v162
	s_waitcnt lgkmcnt(0)
	v_add_f32_e32 v141, v137, v136
	v_lshlrev_b32_e32 v136, 16, v163
	v_add_f32_e32 v142, v138, v136
	v_and_b32_e32 v136, 0xffff0000, v163
	v_add_f32_e32 v139, v139, v136
	v_mul_f32_e32 v136, v141, v141
	v_fmac_f32_e32 v136, v140, v140
	v_fmac_f32_e32 v136, v142, v142
	v_fmac_f32_e32 v136, v139, v139
	s_nop 1
	v_mov_b32_dpp v137, v136 quad_perm:[1,0,3,2] row_mask:0xf bank_mask:0xf
	v_cvt_pk_bf16_f32 v138, v140, v141
	v_cvt_pk_bf16_f32 v139, v142, v139
	global_store_dwordx2 v[190:191], v[138:139], off offset:256
	s_waitcnt lgkmcnt(0)
	v_add_f32_e32 v136, v136, v137
	s_nop 1
	v_mov_b32_dpp v137, v136 quad_perm:[2,3,0,1] row_mask:0xf bank_mask:0xf
	s_waitcnt lgkmcnt(0)
	v_add_f32_e32 v136, v136, v137
	s_nop 1
	v_mov_b32_dpp v137, v136 row_half_mirror row_mask:0xf bank_mask:0xf
	s_and_saveexec_b64 s[6:7], vcc
	s_cbranch_execz .LBB0_440
	s_waitcnt lgkmcnt(0)
	v_add_f32_e32 v136, v136, v137
	global_atomic_add_f32 v[144:145], v136, off offset:64
.LBB0_440:
	s_or_b64 exec, exec, s[6:7]
	s_waitcnt vmcnt(15)
	v_lshlrev_b32_e32 v136, 16, v160
	v_add_f32_e32 v136, v132, v136
	v_and_b32_e32 v132, 0xffff0000, v160
	s_waitcnt lgkmcnt(0)
	v_add_f32_e32 v137, v133, v132
	v_lshlrev_b32_e32 v132, 16, v161
	v_add_f32_e32 v138, v134, v132
	v_and_b32_e32 v132, 0xffff0000, v161
	v_add_f32_e32 v135, v135, v132
	v_mul_f32_e32 v132, v137, v137
	v_fmac_f32_e32 v132, v136, v136
	v_fmac_f32_e32 v132, v138, v138
	v_fmac_f32_e32 v132, v135, v135
	s_nop 1
	v_mov_b32_dpp v133, v132 quad_perm:[1,0,3,2] row_mask:0xf bank_mask:0xf
	v_cvt_pk_bf16_f32 v134, v136, v137
	v_cvt_pk_bf16_f32 v135, v138, v135
	global_store_dwordx2 v[186:187], v[134:135], off offset:256
	s_waitcnt lgkmcnt(0)
	v_add_f32_e32 v132, v132, v133
	s_nop 1
	v_mov_b32_dpp v133, v132 quad_perm:[2,3,0,1] row_mask:0xf bank_mask:0xf
	s_waitcnt lgkmcnt(0)
	v_add_f32_e32 v132, v132, v133
	s_nop 1
	v_mov_b32_dpp v133, v132 row_half_mirror row_mask:0xf bank_mask:0xf
	s_and_saveexec_b64 s[6:7], vcc
	s_cbranch_execz .LBB0_442
	s_waitcnt lgkmcnt(0)
	v_add_f32_e32 v132, v132, v133
	global_atomic_add_f32 v[144:145], v132, off offset:96
.LBB0_442:
	s_or_b64 exec, exec, s[6:7]
	ds_write_b128 v201, v[76:79]
	ds_write_b128 v203, v[72:75]
	s_waitcnt lgkmcnt(2)
	ds_read_b128 v[132:135], v228
	s_waitcnt vmcnt(15)
	v_lshlrev_b32_e32 v140, 16, v158
	ds_write_b128 v201, v[68:71] offset:2048
	ds_write_b128 v203, v[64:67] offset:2048
	ds_read_b128 v[136:139], v228 offset:2048
	s_waitcnt lgkmcnt(3)
	v_add_f32_e32 v160, v132, v140
	v_and_b32_e32 v132, 0xffff0000, v158
	v_add_f32_e32 v161, v133, v132
	v_lshlrev_b32_e32 v132, 16, v159
	v_add_f32_e32 v162, v134, v132
	v_and_b32_e32 v132, 0xffff0000, v159
	v_add_f32_e32 v163, v135, v132
	v_mul_f32_e32 v132, v161, v161
	v_fmac_f32_e32 v132, v160, v160
	v_fmac_f32_e32 v132, v162, v162
	v_fmac_f32_e32 v132, v163, v163
	s_nop 1
	v_mov_b32_dpp v133, v132 quad_perm:[1,0,3,2] row_mask:0xf bank_mask:0xf
	v_cvt_pk_bf16_f32 v160, v160, v161
	v_cvt_pk_bf16_f32 v161, v162, v163
	s_waitcnt lgkmcnt(0)
	v_add_f32_e32 v158, v132, v133
	s_nop 1
	v_mov_b32_dpp v159, v158 quad_perm:[2,3,0,1] row_mask:0xf bank_mask:0xf
	ds_read_b128 v[140:143], v199
	ds_read_b128 v[132:135], v202
	global_store_dwordx2 v[174:175], v[160:161], off offset:256
	s_waitcnt lgkmcnt(2)
	v_add_f32_e32 v158, v158, v159
	s_nop 1
	v_mov_b32_dpp v159, v158 row_half_mirror row_mask:0xf bank_mask:0xf
	s_and_saveexec_b64 s[6:7], vcc
	s_cbranch_execz .LBB0_444
	s_waitcnt lgkmcnt(0)
	v_add_f32_e32 v158, v158, v159
	global_atomic_add_f32 v[144:145], v158, off offset:128
.LBB0_444:
	s_or_b64 exec, exec, s[6:7]
	s_waitcnt vmcnt(15)
	v_lshlrev_b32_e32 v158, 16, v156
	s_waitcnt lgkmcnt(1)
	v_add_f32_e32 v158, v140, v158
	v_and_b32_e32 v140, 0xffff0000, v156
	v_add_f32_e32 v156, v141, v140
	v_lshlrev_b32_e32 v140, 16, v157
	s_waitcnt lgkmcnt(0)
	v_add_f32_e32 v159, v142, v140
	v_and_b32_e32 v140, 0xffff0000, v157
	v_add_f32_e32 v143, v143, v140
	v_mul_f32_e32 v140, v156, v156
	v_fmac_f32_e32 v140, v158, v158
	v_fmac_f32_e32 v140, v159, v159
	v_fmac_f32_e32 v140, v143, v143
	s_nop 1
	v_mov_b32_dpp v141, v140 quad_perm:[1,0,3,2] row_mask:0xf bank_mask:0xf
	v_cvt_pk_bf16_f32 v142, v158, v156
	v_cvt_pk_bf16_f32 v143, v159, v143
	global_store_dwordx2 v[178:179], v[142:143], off offset:256
	s_waitcnt lgkmcnt(0)
	v_add_f32_e32 v140, v140, v141
	s_nop 1
	v_mov_b32_dpp v141, v140 quad_perm:[2,3,0,1] row_mask:0xf bank_mask:0xf
	s_waitcnt lgkmcnt(0)
	v_add_f32_e32 v140, v140, v141
	s_nop 1
	v_mov_b32_dpp v141, v140 row_half_mirror row_mask:0xf bank_mask:0xf
	s_and_saveexec_b64 s[6:7], vcc
	s_cbranch_execz .LBB0_446
	s_waitcnt lgkmcnt(0)
	v_add_f32_e32 v140, v140, v141
	global_atomic_add_f32 v[144:145], v140, off offset:160
; template <int EPI> __device__ __forceinline__ void epi_res(const int tid_e, const GemmArgs& ga, int brow, int bcol, f32x4 (&acc)[2][2][4][2], char* epl) {
;     ...
;     if (EPI != 2) {
; #pragma unroll
;       for (int bj = 0; bj < 2; ++bj)
; #pragma unroll
;         for (int h = 0; h < 2; ++h)
; #pragma unroll
;           for (int i = 0; i < 4; ++i)
;             rb[bj][h][i] = *reinterpret_cast<const u32x2*>(ga.resb + (size_t)(brow + rl0 + ai * 128 + h * 32 + i * 8) * DM + cl0 + bj * 128);
;     }
; #pragma unroll
;     for (int bj = 0; bj < 2; ++bj) {
;       const int col = cl0 + bj * 128;
;       f32x4 scv = {1.f, 1.f, 1.f, 1.f};
;       if (EPI == 3) scv = *reinterpret_cast<const f32x4*>(ga.scale + col);
;       if (EPI == 2) {
; #pragma unroll
;         for (int h = 0; h < 2; ++h)
; #pragma unroll
;           for (int i = 0; i < 4; ++i)
;             rf[h][i] = *reinterpret_cast<const f32x4*>(resf + (size_t)(rl0 + ai * 128 + h * 32 + i * 8) * DM + col);
;       }
; #pragma unroll
;       for (int h = 0; h < 2; ++h) {
; #pragma unroll
;         for (int mm = 0; mm < 2; ++mm) {
;           const int lrow = mm * 16 + fr_e;
; #pragma unroll
;           for (int n = 0; n < 2; ++n)
;             *reinterpret_cast<f32x4*>(sl + lrow * 128 + (((n * 4 + fq_e) ^ ((lrow >> 1) & 7)) * 16)) = acc[ai][bj][h * 2 + mm][n];
;         }
;         f32x4 v[4];
; #pragma unroll
;         for (int i = 0; i < 4; ++i) { const int lrow = i * 8 + rr;
;           v[i] = *reinterpret_cast<const f32x4*>(sl + lrow * 128 + ((rc ^ ((lrow >> 1) & 7)) * 16)); }
; #pragma unroll
;         for (int i = 0; i < 4; ++i) {
;           const int row = brow + rl0 + ai * 128 + h * 32 + i * 8;
;           f32x4 x = v[i];
;           if (EPI == 3) x = x * scv;
;           if (EPI == 2) x = x + rf[h][i];
;           else { const u32x2 r = rb[bj][h][i]; x[0] += bflo(r[0]); x[1] += bfhi(r[0]); x[2] += bflo(r[1]); x[3] += bfhi(r[1]); }
;           if (EPI == 5) *reinterpret_cast<f32x4*>(ga.outf + (size_t)row * DM + col) = x;
;           else {
;             u32x2 w = {cvtpk(x[0], x[1]), cvtpk(x[2], x[3])};
;             *reinterpret_cast<u32x2*>(ga.Cb + (size_t)row * DM + col) = w;
;             float ss = x[0] * x[0] + x[1] * x[1] + x[2] * x[2] + x[3] * x[3];
;             ss += __shfl_xor(ss, 1); ss += __shfl_xor(ss, 2); ss += __shfl_xor(ss, 4);
.LBB0_446:
	s_or_b64 exec, exec, s[6:7]
	s_waitcnt vmcnt(15)
	v_lshlrev_b32_e32 v140, 16, v154
	v_add_f32_e32 v140, v136, v140
	v_and_b32_e32 v136, 0xffff0000, v154
	s_waitcnt lgkmcnt(0)
	v_add_f32_e32 v141, v137, v136
	v_lshlrev_b32_e32 v136, 16, v155
	v_add_f32_e32 v142, v138, v136
	v_and_b32_e32 v136, 0xffff0000, v155
	v_add_f32_e32 v139, v139, v136
	v_mul_f32_e32 v136, v141, v141
	v_fmac_f32_e32 v136, v140, v140
	v_fmac_f32_e32 v136, v142, v142
	v_fmac_f32_e32 v136, v139, v139
	s_nop 1
	v_mov_b32_dpp v137, v136 quad_perm:[1,0,3,2] row_mask:0xf bank_mask:0xf
	v_cvt_pk_bf16_f32 v138, v140, v141
	v_cvt_pk_bf16_f32 v139, v142, v139
	global_store_dwordx2 v[172:173], v[138:139], off offset:256
	s_waitcnt lgkmcnt(0)
	v_add_f32_e32 v136, v136, v137
	s_nop 1
	v_mov_b32_dpp v137, v136 quad_perm:[2,3,0,1] row_mask:0xf bank_mask:0xf
	s_waitcnt lgkmcnt(0)
	v_add_f32_e32 v136, v136, v137
	s_nop 1
	v_mov_b32_dpp v137, v136 row_half_mirror row_mask:0xf bank_mask:0xf
	s_and_saveexec_b64 s[6:7], vcc
	s_cbranch_execz .LBB0_448
	s_waitcnt lgkmcnt(0)
	v_add_f32_e32 v136, v136, v137
	global_atomic_add_f32 v[144:145], v136, off offset:192
.LBB0_448:
	s_or_b64 exec, exec, s[6:7]
	s_waitcnt vmcnt(15)
	v_lshlrev_b32_e32 v136, 16, v152
	v_add_f32_e32 v136, v132, v136
	v_and_b32_e32 v132, 0xffff0000, v152
	s_waitcnt lgkmcnt(0)
	v_add_f32_e32 v137, v133, v132
	v_lshlrev_b32_e32 v132, 16, v153
	v_add_f32_e32 v138, v134, v132
	v_and_b32_e32 v132, 0xffff0000, v153
	v_add_f32_e32 v135, v135, v132
	v_mul_f32_e32 v132, v137, v137
	v_fmac_f32_e32 v132, v136, v136
	v_fmac_f32_e32 v132, v138, v138
	v_fmac_f32_e32 v132, v135, v135
	s_nop 1
	v_mov_b32_dpp v133, v132 quad_perm:[1,0,3,2] row_mask:0xf bank_mask:0xf
	v_cvt_pk_bf16_f32 v134, v136, v137
	v_cvt_pk_bf16_f32 v135, v138, v135
	global_store_dwordx2 v[168:169], v[134:135], off offset:256
	s_waitcnt lgkmcnt(0)
	v_add_f32_e32 v132, v132, v133
	s_nop 1
	v_mov_b32_dpp v133, v132 quad_perm:[2,3,0,1] row_mask:0xf bank_mask:0xf
	s_waitcnt lgkmcnt(0)
	v_add_f32_e32 v132, v132, v133
	s_nop 1
	v_mov_b32_dpp v133, v132 row_half_mirror row_mask:0xf bank_mask:0xf
	s_and_saveexec_b64 s[6:7], vcc
	s_cbranch_execz .LBB0_450
	s_waitcnt lgkmcnt(0)
	v_add_f32_e32 v132, v132, v133
	global_atomic_add_f32 v[144:145], v132, off offset:224
.LBB0_450:
	s_or_b64 exec, exec, s[6:7]
	v_lshl_add_u64 v[166:167], v[148:149], 0, s[80:81]
	s_waitcnt lgkmcnt(0)
	v_lshl_add_u64 v[132:133], v[146:147], 0, v[166:167]
	global_load_dwordx2 v[140:141], v[132:133], off
	s_mov_b64 s[6:7], 0xa0000
	v_lshl_add_u64 v[174:175], v[148:149], 0, s[6:7]
	v_lshl_add_u64 v[168:169], v[148:149], 0, s[82:83]
	v_lshl_add_u64 v[170:171], v[148:149], 0, s[84:85]
	v_lshl_add_u64 v[172:173], v[148:149], 0, s[86:87]
	v_lshl_add_u64 v[176:177], v[148:149], 0, s[88:89]
	v_lshl_add_u64 v[178:179], v[148:149], 0, s[90:91]
	v_lshl_add_u64 v[164:165], v[148:149], 0, s[92:93]
	v_lshl_add_u64 v[134:135], v[146:147], 0, v[168:169]
	v_lshl_add_u64 v[136:137], v[146:147], 0, v[170:171]
	v_lshl_add_u64 v[138:139], v[146:147], 0, v[172:173]
	v_lshl_add_u64 v[142:143], v[146:147], 0, v[174:175]
	v_lshl_add_u64 v[148:149], v[146:147], 0, v[176:177]
	v_lshl_add_u64 v[194:195], v[146:147], 0, v[178:179]
	v_lshl_add_u64 v[146:147], v[146:147], 0, v[164:165]
	global_load_dwordx2 v[192:193], v[134:135], off
	global_load_dwordx2 v[160:161], v[134:135], off offset:256
	global_load_dwordx2 v[162:163], v[132:133], off offset:256
	global_load_dwordx2 v[190:191], v[136:137], off
	global_load_dwordx2 v[188:189], v[138:139], off
	global_load_dwordx2 v[156:157], v[138:139], off offset:256
	global_load_dwordx2 v[158:159], v[136:137], off offset:256
	global_load_dwordx2 v[186:187], v[142:143], off
	global_load_dwordx2 v[184:185], v[148:149], off
	global_load_dwordx2 v[152:153], v[148:149], off offset:256
	global_load_dwordx2 v[154:155], v[142:143], off offset:256
	global_load_dwordx2 v[182:183], v[194:195], off
	global_load_dwordx2 v[180:181], v[146:147], off
	s_nop 0
	global_load_dwordx2 v[146:147], v[146:147], off offset:256
	s_nop 0
	global_load_dwordx2 v[148:149], v[194:195], off offset:256
	ds_write_b128 v201, v[60:63]
	ds_write_b128 v203, v[56:59]
	ds_write_b128 v201, v[52:55] offset:2048
	ds_write_b128 v203, v[48:51] offset:2048
	ds_read_b128 v[132:135], v228
	ds_read_b128 v[136:139], v228 offset:2048
	v_lshl_add_u64 v[166:167], s[96:97], 0, v[166:167]
	v_lshl_add_u64 v[166:167], v[98:99], 1, v[166:167]
	s_waitcnt vmcnt(15)
	v_lshlrev_b32_e32 v142, 16, v140
	v_and_b32_e32 v140, 0xffff0000, v140
	s_waitcnt lgkmcnt(1)
	v_add_f32_e32 v195, v133, v140
	v_lshlrev_b32_e32 v143, 16, v141
	v_add_f32_e32 v194, v132, v142
	v_mul_f32_e32 v132, v195, v195
	v_and_b32_e32 v141, 0xffff0000, v141
	v_add_f32_e32 v197, v134, v143
	v_fmac_f32_e32 v132, v194, v194
	v_add_f32_e32 v229, v135, v141
	v_fmac_f32_e32 v132, v197, v197
	v_fmac_f32_e32 v132, v229, v229
	s_nop 1
	v_mov_b32_dpp v133, v132 quad_perm:[1,0,3,2] row_mask:0xf bank_mask:0xf
	v_cvt_pk_bf16_f32 v196, v194, v195
	v_cvt_pk_bf16_f32 v197, v197, v229
	s_waitcnt lgkmcnt(0)
	v_add_f32_e32 v230, v132, v133
	s_nop 1
	v_mov_b32_dpp v231, v230 quad_perm:[2,3,0,1] row_mask:0xf bank_mask:0xf
	ds_read_b128 v[140:143], v199
	ds_read_b128 v[132:135], v202
	global_store_dwordx2 v[166:167], v[196:197], off
	s_waitcnt lgkmcnt(2)
	v_add_f32_e32 v194, v230, v231
	s_nop 1
	v_mov_b32_dpp v195, v194 row_half_mirror row_mask:0xf bank_mask:0xf
	s_and_saveexec_b64 s[6:7], vcc
	s_cbranch_execz .LBB0_452
	s_waitcnt lgkmcnt(0)
	v_add_f32_e32 v194, v194, v195
	global_atomic_add_f32 v[144:145], v194, off offset:512
; __device__ __forceinline__ float bflo(unsigned w) { return __uint_as_float(w << 16); }
; __device__ __forceinline__ float bfhi(unsigned w) { return __uint_as_float(w & 0xffff0000u); }
; template <int EPI> __device__ __forceinline__ void epi_res(const int tid_e, const GemmArgs& ga, int brow, int bcol, f32x4 (&acc)[2][2][4][2], char* epl) {
;     ...
;       for (int h = 0; h < 2; ++h) {
; #pragma unroll
;         for (int mm = 0; mm < 2; ++mm) {
;           const int lrow = mm * 16 + fr_e;
; #pragma unroll
;           for (int n = 0; n < 2; ++n)
;             *reinterpret_cast<f32x4*>(sl + lrow * 128 + (((n * 4 + fq_e) ^ ((lrow >> 1) & 7)) * 16)) = acc[ai][bj][h * 2 + mm][n];
;         }
;         f32x4 v[4];
; #pragma unroll
;         for (int i = 0; i < 4; ++i) { const int lrow = i * 8 + rr;
;           v[i] = *reinterpret_cast<const f32x4*>(sl + lrow * 128 + ((rc ^ ((lrow >> 1) & 7)) * 16)); }
; #pragma unroll
;         for (int i = 0; i < 4; ++i) {
;           const int row = brow + rl0 + ai * 128 + h * 32 + i * 8;
;           f32x4 x = v[i];
;           if (EPI == 3) x = x * scv;
;           if (EPI == 2) x = x + rf[h][i];
;           else { const u32x2 r = rb[bj][h][i]; x[0] += bflo(r[0]); x[1] += bfhi(r[0]); x[2] += bflo(r[1]); x[3] += bfhi(r[1]); }
;           if (EPI == 5) *reinterpret_cast<f32x4*>(ga.outf + (size_t)row * DM + col) = x;
;           else {
;             u32x2 w = {cvtpk(x[0], x[1]), cvtpk(x[2], x[3])};
;             *reinterpret_cast<u32x2*>(ga.Cb + (size_t)row * DM + col) = w;
;             float ss = x[0] * x[0] + x[1] * x[1] + x[2] * x[2] + x[3] * x[3];
;             ss += __shfl_xor(ss, 1); ss += __shfl_xor(ss, 2); ss += __shfl_xor(ss, 4);
;             if (rc == 0) atomicAdd(ga.rss_out + row, ss);
;           }
.LBB0_452:
	s_or_b64 exec, exec, s[6:7]
	s_waitcnt vmcnt(15)
	v_lshlrev_b32_e32 v194, 16, v192
	v_and_b32_e32 v192, 0xffff0000, v192
	s_waitcnt lgkmcnt(1)
	v_add_f32_e32 v141, v141, v192
	v_lshlrev_b32_e32 v192, 16, v193
	v_add_f32_e32 v192, v142, v192
	v_and_b32_e32 v142, 0xffff0000, v193
	v_add_f32_e32 v140, v140, v194
	v_add_f32_e32 v143, v143, v142
	v_mul_f32_e32 v142, v141, v141
	v_fmac_f32_e32 v142, v140, v140
	v_fmac_f32_e32 v142, v192, v192
	v_fmac_f32_e32 v142, v143, v143
	s_nop 1
	v_mov_b32_dpp v193, v142 quad_perm:[1,0,3,2] row_mask:0xf bank_mask:0xf
	v_lshl_add_u64 v[168:169], s[96:97], 0, v[168:169]
	v_lshl_add_u64 v[168:169], v[98:99], 1, v[168:169]
	v_cvt_pk_bf16_f32 v143, v192, v143
	s_waitcnt lgkmcnt(0)
	v_add_f32_e32 v193, v142, v193
	s_nop 1
	v_mov_b32_dpp v194, v193 quad_perm:[2,3,0,1] row_mask:0xf bank_mask:0xf
	v_cvt_pk_bf16_f32 v142, v140, v141
	global_store_dwordx2 v[168:169], v[142:143], off
	s_waitcnt lgkmcnt(0)
	v_add_f32_e32 v140, v193, v194
	s_nop 1
	v_mov_b32_dpp v141, v140 row_half_mirror row_mask:0xf bank_mask:0xf
	s_and_saveexec_b64 s[6:7], vcc
	s_cbranch_execz .LBB0_454
	s_waitcnt lgkmcnt(0)
	v_add_f32_e32 v140, v140, v141
	global_atomic_add_f32 v[144:145], v140, off offset:544
.LBB0_454:
	s_or_b64 exec, exec, s[6:7]
	s_waitcnt vmcnt(13)
	v_lshlrev_b32_e32 v140, 16, v190
	v_add_f32_e32 v136, v136, v140
	v_and_b32_e32 v140, 0xffff0000, v190
	v_add_f32_e32 v137, v137, v140
	v_lshlrev_b32_e32 v140, 16, v191
	v_add_f32_e32 v140, v138, v140
	v_and_b32_e32 v138, 0xffff0000, v191
	v_add_f32_e32 v139, v139, v138
	v_mul_f32_e32 v138, v137, v137
	v_fmac_f32_e32 v138, v136, v136
	v_fmac_f32_e32 v138, v140, v140
	v_fmac_f32_e32 v138, v139, v139
	s_waitcnt lgkmcnt(0)
	s_nop 1
	v_mov_b32_dpp v141, v138 quad_perm:[1,0,3,2] row_mask:0xf bank_mask:0xf
	v_cvt_pk_bf16_f32 v139, v140, v139
	s_waitcnt lgkmcnt(0)
	v_add_f32_e32 v141, v138, v141
	s_nop 1
	v_mov_b32_dpp v142, v141 quad_perm:[2,3,0,1] row_mask:0xf bank_mask:0xf
	v_cvt_pk_bf16_f32 v138, v136, v137
	s_waitcnt lgkmcnt(0)
	v_add_f32_e32 v136, v141, v142
	s_nop 1
	v_mov_b32_dpp v137, v136 row_half_mirror row_mask:0xf bank_mask:0xf
	v_lshl_add_u64 v[140:141], s[96:97], 0, v[170:171]
	v_lshl_add_u64 v[170:171], v[98:99], 1, v[140:141]
	global_store_dwordx2 v[170:171], v[138:139], off
	s_and_saveexec_b64 s[6:7], vcc
	s_cbranch_execz .LBB0_456
	s_waitcnt lgkmcnt(0)
	v_add_f32_e32 v136, v136, v137
	global_atomic_add_f32 v[144:145], v136, off offset:576
.LBB0_456:
	s_or_b64 exec, exec, s[6:7]
	s_waitcnt vmcnt(13)
	v_lshlrev_b32_e32 v136, 16, v188
	v_add_f32_e32 v132, v132, v136
	v_and_b32_e32 v136, 0xffff0000, v188
	v_add_f32_e32 v133, v133, v136
	v_lshlrev_b32_e32 v136, 16, v189
	v_add_f32_e32 v136, v134, v136
	v_and_b32_e32 v134, 0xffff0000, v189
	v_add_f32_e32 v135, v135, v134
	v_mul_f32_e32 v134, v133, v133
	v_fmac_f32_e32 v134, v132, v132
	v_fmac_f32_e32 v134, v136, v136
	v_fmac_f32_e32 v134, v135, v135
	s_waitcnt lgkmcnt(0)
	s_nop 1
	v_mov_b32_dpp v137, v134 quad_perm:[1,0,3,2] row_mask:0xf bank_mask:0xf
	v_cvt_pk_bf16_f32 v135, v136, v135
	s_waitcnt lgkmcnt(0)
	v_add_f32_e32 v137, v134, v137
	s_nop 1
	v_mov_b32_dpp v138, v137 quad_perm:[2,3,0,1] row_mask:0xf bank_mask:0xf
	v_cvt_pk_bf16_f32 v134, v132, v133
	s_waitcnt lgkmcnt(0)
	v_add_f32_e32 v132, v137, v138
	s_nop 1
	v_mov_b32_dpp v133, v132 row_half_mirror row_mask:0xf bank_mask:0xf
	v_lshl_add_u64 v[136:137], s[96:97], 0, v[172:173]
	v_lshl_add_u64 v[172:173], v[98:99], 1, v[136:137]
	global_store_dwordx2 v[172:173], v[134:135], off
	s_and_saveexec_b64 s[6:7], vcc
	s_cbranch_execz .LBB0_458
	s_waitcnt lgkmcnt(0)
	v_add_f32_e32 v132, v132, v133
	global_atomic_add_f32 v[144:145], v132, off offset:608
.LBB0_458:
	s_or_b64 exec, exec, s[6:7]
	ds_write_b128 v201, v[44:47]
	ds_write_b128 v203, v[40:43]
	s_waitcnt lgkmcnt(2)
	ds_read_b128 v[132:135], v228
	s_waitcnt vmcnt(11)
	v_lshlrev_b32_e32 v140, 16, v186
	ds_write_b128 v201, v[36:39] offset:2048
	ds_write_b128 v203, v[32:35] offset:2048
	ds_read_b128 v[136:139], v228 offset:2048
	v_lshl_add_u64 v[174:175], s[96:97], 0, v[174:175]
	s_waitcnt lgkmcnt(3)
	v_add_f32_e32 v188, v132, v140
	v_and_b32_e32 v132, 0xffff0000, v186
	v_add_f32_e32 v186, v133, v132
	v_lshlrev_b32_e32 v132, 16, v187
	v_add_f32_e32 v189, v134, v132
	v_and_b32_e32 v132, 0xffff0000, v187
	v_add_f32_e32 v190, v135, v132
	v_mul_f32_e32 v132, v186, v186
	v_fmac_f32_e32 v132, v188, v188
	v_fmac_f32_e32 v132, v189, v189
	v_fmac_f32_e32 v132, v190, v190
	s_nop 1
	v_mov_b32_dpp v133, v132 quad_perm:[1,0,3,2] row_mask:0xf bank_mask:0xf
	v_cvt_pk_bf16_f32 v188, v188, v186
	v_lshl_add_u64 v[174:175], v[98:99], 1, v[174:175]
	v_cvt_pk_bf16_f32 v189, v189, v190
	s_waitcnt lgkmcnt(0)
	v_add_f32_e32 v187, v132, v133
	s_nop 1
	v_mov_b32_dpp v191, v187 quad_perm:[2,3,0,1] row_mask:0xf bank_mask:0xf
	ds_read_b128 v[140:143], v199
	ds_read_b128 v[132:135], v202
	global_store_dwordx2 v[174:175], v[188:189], off
	s_waitcnt lgkmcnt(2)
	v_add_f32_e32 v186, v187, v191
	s_nop 1
	v_mov_b32_dpp v187, v186 row_half_mirror row_mask:0xf bank_mask:0xf
	s_and_saveexec_b64 s[6:7], vcc
	s_cbranch_execz .LBB0_460
	s_waitcnt lgkmcnt(0)
	v_add_f32_e32 v186, v186, v187
	global_atomic_add_f32 v[144:145], v186, off offset:640
; __device__ __forceinline__ float bflo(unsigned w) { return __uint_as_float(w << 16); }
; __device__ __forceinline__ float bfhi(unsigned w) { return __uint_as_float(w & 0xffff0000u); }
; template <int EPI> __device__ __forceinline__ void epi_res(const int tid_e, const GemmArgs& ga, int brow, int bcol, f32x4 (&acc)[2][2][4][2], char* epl) {
;     ...
;         f32x4 v[4];
; #pragma unroll
;         for (int i = 0; i < 4; ++i) { const int lrow = i * 8 + rr;
;           v[i] = *reinterpret_cast<const f32x4*>(sl + lrow * 128 + ((rc ^ ((lrow >> 1) & 7)) * 16)); }
; #pragma unroll
;         for (int i = 0; i < 4; ++i) {
;           const int row = brow + rl0 + ai * 128 + h * 32 + i * 8;
;           f32x4 x = v[i];
;           if (EPI == 3) x = x * scv;
;           if (EPI == 2) x = x + rf[h][i];
;           else { const u32x2 r = rb[bj][h][i]; x[0] += bflo(r[0]); x[1] += bfhi(r[0]); x[2] += bflo(r[1]); x[3] += bfhi(r[1]); }
;           if (EPI == 5) *reinterpret_cast<f32x4*>(ga.outf + (size_t)row * DM + col) = x;
;           else {
;             u32x2 w = {cvtpk(x[0], x[1]), cvtpk(x[2], x[3])};
;             *reinterpret_cast<u32x2*>(ga.Cb + (size_t)row * DM + col) = w;
;             float ss = x[0] * x[0] + x[1] * x[1] + x[2] * x[2] + x[3] * x[3];
;             ss += __shfl_xor(ss, 1); ss += __shfl_xor(ss, 2); ss += __shfl_xor(ss, 4);
;             if (rc == 0) atomicAdd(ga.rss_out + row, ss);
;           }
;         }
.LBB0_460:
	s_or_b64 exec, exec, s[6:7]
	s_waitcnt vmcnt(11)
	v_lshlrev_b32_e32 v186, 16, v184
	v_and_b32_e32 v184, 0xffff0000, v184
	s_waitcnt lgkmcnt(1)
	v_add_f32_e32 v141, v141, v184
	v_lshlrev_b32_e32 v184, 16, v185
	v_add_f32_e32 v184, v142, v184
	v_and_b32_e32 v142, 0xffff0000, v185
	v_add_f32_e32 v140, v140, v186
	v_add_f32_e32 v143, v143, v142
	v_mul_f32_e32 v142, v141, v141
	v_fmac_f32_e32 v142, v140, v140
	v_fmac_f32_e32 v142, v184, v184
	v_fmac_f32_e32 v142, v143, v143
	s_nop 1
	v_mov_b32_dpp v185, v142 quad_perm:[1,0,3,2] row_mask:0xf bank_mask:0xf
	v_lshl_add_u64 v[176:177], s[96:97], 0, v[176:177]
	v_lshl_add_u64 v[176:177], v[98:99], 1, v[176:177]
	v_cvt_pk_bf16_f32 v143, v184, v143
	s_waitcnt lgkmcnt(0)
	v_add_f32_e32 v185, v142, v185
	s_nop 1
	v_mov_b32_dpp v186, v185 quad_perm:[2,3,0,1] row_mask:0xf bank_mask:0xf
	v_cvt_pk_bf16_f32 v142, v140, v141
	global_store_dwordx2 v[176:177], v[142:143], off
	s_waitcnt lgkmcnt(0)
	v_add_f32_e32 v140, v185, v186
	s_nop 1
	v_mov_b32_dpp v141, v140 row_half_mirror row_mask:0xf bank_mask:0xf
	s_and_saveexec_b64 s[6:7], vcc
	s_cbranch_execz .LBB0_462
	s_waitcnt lgkmcnt(0)
	v_add_f32_e32 v140, v140, v141
	global_atomic_add_f32 v[144:145], v140, off offset:672
.LBB0_462:
	s_or_b64 exec, exec, s[6:7]
	s_waitcnt vmcnt(9)
	v_lshlrev_b32_e32 v140, 16, v182
	v_add_f32_e32 v136, v136, v140
	v_and_b32_e32 v140, 0xffff0000, v182
	v_add_f32_e32 v137, v137, v140
	v_lshlrev_b32_e32 v140, 16, v183
	v_add_f32_e32 v140, v138, v140
	v_and_b32_e32 v138, 0xffff0000, v183
	v_add_f32_e32 v139, v139, v138
	v_mul_f32_e32 v138, v137, v137
	v_fmac_f32_e32 v138, v136, v136
	v_fmac_f32_e32 v138, v140, v140
	v_fmac_f32_e32 v138, v139, v139
	s_waitcnt lgkmcnt(0)
	s_nop 1
	v_mov_b32_dpp v141, v138 quad_perm:[1,0,3,2] row_mask:0xf bank_mask:0xf
	v_cvt_pk_bf16_f32 v139, v140, v139
	s_waitcnt lgkmcnt(0)
	v_add_f32_e32 v141, v138, v141
	s_nop 1
	v_mov_b32_dpp v142, v141 quad_perm:[2,3,0,1] row_mask:0xf bank_mask:0xf
	v_cvt_pk_bf16_f32 v138, v136, v137
	s_waitcnt lgkmcnt(0)
	v_add_f32_e32 v136, v141, v142
	s_nop 1
	v_mov_b32_dpp v137, v136 row_half_mirror row_mask:0xf bank_mask:0xf
	v_lshl_add_u64 v[140:141], s[96:97], 0, v[178:179]
	v_lshl_add_u64 v[178:179], v[98:99], 1, v[140:141]
	global_store_dwordx2 v[178:179], v[138:139], off
	s_and_saveexec_b64 s[6:7], vcc
	s_cbranch_execz .LBB0_464
	s_waitcnt lgkmcnt(0)
	v_add_f32_e32 v136, v136, v137
	global_atomic_add_f32 v[144:145], v136, off offset:704
.LBB0_464:
	s_or_b64 exec, exec, s[6:7]
	s_waitcnt vmcnt(9)
	v_lshlrev_b32_e32 v136, 16, v180
	v_add_f32_e32 v132, v132, v136
	v_and_b32_e32 v136, 0xffff0000, v180
	v_add_f32_e32 v133, v133, v136
	v_lshlrev_b32_e32 v136, 16, v181
	v_add_f32_e32 v136, v134, v136
	v_and_b32_e32 v134, 0xffff0000, v181
	v_add_f32_e32 v135, v135, v134
	v_mul_f32_e32 v134, v133, v133
	v_fmac_f32_e32 v134, v132, v132
	v_fmac_f32_e32 v134, v136, v136
	v_fmac_f32_e32 v134, v135, v135
	s_waitcnt lgkmcnt(0)
	s_nop 1
	v_mov_b32_dpp v137, v134 quad_perm:[1,0,3,2] row_mask:0xf bank_mask:0xf
	v_cvt_pk_bf16_f32 v135, v136, v135
	s_waitcnt lgkmcnt(0)
	v_add_f32_e32 v137, v134, v137
	s_nop 1
	v_mov_b32_dpp v138, v137 quad_perm:[2,3,0,1] row_mask:0xf bank_mask:0xf
	v_cvt_pk_bf16_f32 v134, v132, v133
	s_waitcnt lgkmcnt(0)
	v_add_f32_e32 v132, v137, v138
	s_nop 1
	v_mov_b32_dpp v133, v132 row_half_mirror row_mask:0xf bank_mask:0xf
	v_lshl_add_u64 v[136:137], s[96:97], 0, v[164:165]
	v_lshl_add_u64 v[98:99], v[98:99], 1, v[136:137]
	global_store_dwordx2 v[98:99], v[134:135], off
	s_and_saveexec_b64 s[6:7], vcc
	s_cbranch_execz .LBB0_466
	s_waitcnt lgkmcnt(0)
	v_add_f32_e32 v132, v132, v133
	global_atomic_add_f32 v[144:145], v132, off offset:736
.LBB0_466:
	s_or_b64 exec, exec, s[6:7]
	ds_write_b128 v201, v[28:31]
	ds_write_b128 v203, v[24:27]
	s_waitcnt lgkmcnt(2)
	ds_read_b128 v[132:135], v228
	v_lshlrev_b32_e32 v140, 16, v162
	ds_write_b128 v201, v[20:23] offset:2048
	ds_write_b128 v203, v[16:19] offset:2048
	ds_read_b128 v[136:139], v228 offset:2048
	s_waitcnt lgkmcnt(3)
	v_add_f32_e32 v164, v132, v140
	v_and_b32_e32 v132, 0xffff0000, v162
	v_add_f32_e32 v165, v133, v132
	v_lshlrev_b32_e32 v132, 16, v163
	v_add_f32_e32 v180, v134, v132
	v_and_b32_e32 v132, 0xffff0000, v163
	v_add_f32_e32 v181, v135, v132
	v_mul_f32_e32 v132, v165, v165
	v_fmac_f32_e32 v132, v164, v164
	v_fmac_f32_e32 v132, v180, v180
	v_fmac_f32_e32 v132, v181, v181
	s_nop 1
	v_mov_b32_dpp v133, v132 quad_perm:[1,0,3,2] row_mask:0xf bank_mask:0xf
	v_cvt_pk_bf16_f32 v164, v164, v165
	v_cvt_pk_bf16_f32 v165, v180, v181
	s_waitcnt lgkmcnt(0)
	v_add_f32_e32 v162, v132, v133
	s_nop 1
	v_mov_b32_dpp v163, v162 quad_perm:[2,3,0,1] row_mask:0xf bank_mask:0xf
	ds_read_b128 v[140:143], v199
	ds_read_b128 v[132:135], v202
	global_store_dwordx2 v[166:167], v[164:165], off offset:256
	s_waitcnt lgkmcnt(2)
	v_add_f32_e32 v162, v162, v163
	s_nop 1
	v_mov_b32_dpp v163, v162 row_half_mirror row_mask:0xf bank_mask:0xf
	s_and_saveexec_b64 s[6:7], vcc
	s_cbranch_execz .LBB0_468
	s_waitcnt lgkmcnt(0)
	v_add_f32_e32 v162, v162, v163
	global_atomic_add_f32 v[144:145], v162, off offset:512
; __device__ __forceinline__ float bflo(unsigned w) { return __uint_as_float(w << 16); }
; __device__ __forceinline__ float bfhi(unsigned w) { return __uint_as_float(w & 0xffff0000u); }
; template <int EPI> __device__ __forceinline__ void epi_res(const int tid_e, const GemmArgs& ga, int brow, int bcol, f32x4 (&acc)[2][2][4][2], char* epl) {
;     ...
;         f32x4 v[4];
; #pragma unroll
;         for (int i = 0; i < 4; ++i) { const int lrow = i * 8 + rr;
;           v[i] = *reinterpret_cast<const f32x4*>(sl + lrow * 128 + ((rc ^ ((lrow >> 1) & 7)) * 16)); }
; #pragma unroll
;         for (int i = 0; i < 4; ++i) {
;           const int row = brow + rl0 + ai * 128 + h * 32 + i * 8;
;           f32x4 x = v[i];
;           if (EPI == 3) x = x * scv;
;           if (EPI == 2) x = x + rf[h][i];
;           else { const u32x2 r = rb[bj][h][i]; x[0] += bflo(r[0]); x[1] += bfhi(r[0]); x[2] += bflo(r[1]); x[3] += bfhi(r[1]); }
;           if (EPI == 5) *reinterpret_cast<f32x4*>(ga.outf + (size_t)row * DM + col) = x;
;           else {
;             u32x2 w = {cvtpk(x[0], x[1]), cvtpk(x[2], x[3])};
;             *reinterpret_cast<u32x2*>(ga.Cb + (size_t)row * DM + col) = w;
;             float ss = x[0] * x[0] + x[1] * x[1] + x[2] * x[2] + x[3] * x[3];
;             ss += __shfl_xor(ss, 1); ss += __shfl_xor(ss, 2); ss += __shfl_xor(ss, 4);
;             if (rc == 0) atomicAdd(ga.rss_out + row, ss);
;           }
;         }
.LBB0_468:
	s_or_b64 exec, exec, s[6:7]
	v_lshlrev_b32_e32 v162, 16, v160
	s_waitcnt lgkmcnt(1)
	v_add_f32_e32 v162, v140, v162
	v_and_b32_e32 v140, 0xffff0000, v160
	v_add_f32_e32 v160, v141, v140
	v_lshlrev_b32_e32 v140, 16, v161
	s_waitcnt lgkmcnt(0)
	v_add_f32_e32 v163, v142, v140
	v_and_b32_e32 v140, 0xffff0000, v161
	v_add_f32_e32 v143, v143, v140
	v_mul_f32_e32 v140, v160, v160
	v_fmac_f32_e32 v140, v162, v162
	v_fmac_f32_e32 v140, v163, v163
	v_fmac_f32_e32 v140, v143, v143
	s_nop 1
	v_mov_b32_dpp v141, v140 quad_perm:[1,0,3,2] row_mask:0xf bank_mask:0xf
	v_cvt_pk_bf16_f32 v142, v162, v160
	v_cvt_pk_bf16_f32 v143, v163, v143
	global_store_dwordx2 v[168:169], v[142:143], off offset:256
	s_waitcnt lgkmcnt(0)
	v_add_f32_e32 v140, v140, v141
	s_nop 1
	v_mov_b32_dpp v141, v140 quad_perm:[2,3,0,1] row_mask:0xf bank_mask:0xf
	s_waitcnt lgkmcnt(0)
	v_add_f32_e32 v140, v140, v141
	s_nop 1
	v_mov_b32_dpp v141, v140 row_half_mirror row_mask:0xf bank_mask:0xf
	s_and_saveexec_b64 s[6:7], vcc
	s_cbranch_execz .LBB0_470
	s_waitcnt lgkmcnt(0)
	v_add_f32_e32 v140, v140, v141
	global_atomic_add_f32 v[144:145], v140, off offset:544
.LBB0_470:
	s_or_b64 exec, exec, s[6:7]
	v_lshlrev_b32_e32 v140, 16, v158
	v_add_f32_e32 v140, v136, v140
	v_and_b32_e32 v136, 0xffff0000, v158
	s_waitcnt lgkmcnt(0)
	v_add_f32_e32 v141, v137, v136
	v_lshlrev_b32_e32 v136, 16, v159
	v_add_f32_e32 v142, v138, v136
	v_and_b32_e32 v136, 0xffff0000, v159
	v_add_f32_e32 v139, v139, v136
	v_mul_f32_e32 v136, v141, v141
	v_fmac_f32_e32 v136, v140, v140
	v_fmac_f32_e32 v136, v142, v142
	v_fmac_f32_e32 v136, v139, v139
	s_nop 1
	v_mov_b32_dpp v137, v136 quad_perm:[1,0,3,2] row_mask:0xf bank_mask:0xf
	v_cvt_pk_bf16_f32 v138, v140, v141
	v_cvt_pk_bf16_f32 v139, v142, v139
	global_store_dwordx2 v[170:171], v[138:139], off offset:256
	s_waitcnt lgkmcnt(0)
	v_add_f32_e32 v136, v136, v137
	s_nop 1
	v_mov_b32_dpp v137, v136 quad_perm:[2,3,0,1] row_mask:0xf bank_mask:0xf
	s_waitcnt lgkmcnt(0)
	v_add_f32_e32 v136, v136, v137
	s_nop 1
	v_mov_b32_dpp v137, v136 row_half_mirror row_mask:0xf bank_mask:0xf
	s_and_saveexec_b64 s[6:7], vcc
	s_cbranch_execz .LBB0_472
	s_waitcnt lgkmcnt(0)
	v_add_f32_e32 v136, v136, v137
	global_atomic_add_f32 v[144:145], v136, off offset:576
.LBB0_472:
	s_or_b64 exec, exec, s[6:7]
	v_lshlrev_b32_e32 v136, 16, v156
	v_add_f32_e32 v136, v132, v136
	v_and_b32_e32 v132, 0xffff0000, v156
	s_waitcnt lgkmcnt(0)
	v_add_f32_e32 v137, v133, v132
	v_lshlrev_b32_e32 v132, 16, v157
	v_add_f32_e32 v138, v134, v132
	v_and_b32_e32 v132, 0xffff0000, v157
	v_add_f32_e32 v135, v135, v132
	v_mul_f32_e32 v132, v137, v137
	v_fmac_f32_e32 v132, v136, v136
	v_fmac_f32_e32 v132, v138, v138
	v_fmac_f32_e32 v132, v135, v135
	s_nop 1
	v_mov_b32_dpp v133, v132 quad_perm:[1,0,3,2] row_mask:0xf bank_mask:0xf
	v_cvt_pk_bf16_f32 v134, v136, v137
	v_cvt_pk_bf16_f32 v135, v138, v135
	global_store_dwordx2 v[172:173], v[134:135], off offset:256
	s_waitcnt lgkmcnt(0)
	v_add_f32_e32 v132, v132, v133
	s_nop 1
	v_mov_b32_dpp v133, v132 quad_perm:[2,3,0,1] row_mask:0xf bank_mask:0xf
	s_waitcnt lgkmcnt(0)
	v_add_f32_e32 v132, v132, v133
	s_nop 1
	v_mov_b32_dpp v133, v132 row_half_mirror row_mask:0xf bank_mask:0xf
	s_and_saveexec_b64 s[6:7], vcc
	s_cbranch_execz .LBB0_474
	s_waitcnt lgkmcnt(0)
	v_add_f32_e32 v132, v132, v133
	global_atomic_add_f32 v[144:145], v132, off offset:608
.LBB0_474:
	s_or_b64 exec, exec, s[6:7]
	ds_write_b128 v201, v[12:15]
	ds_write_b128 v203, v[8:11]
	s_waitcnt lgkmcnt(2)
	ds_read_b128 v[132:135], v228
	v_lshlrev_b32_e32 v140, 16, v154
	ds_write_b128 v201, v[4:7] offset:2048
	ds_write_b128 v203, v[0:3] offset:2048
	ds_read_b128 v[136:139], v228 offset:2048
	s_waitcnt lgkmcnt(3)
	v_add_f32_e32 v156, v132, v140
	v_and_b32_e32 v132, 0xffff0000, v154
	v_add_f32_e32 v157, v133, v132
	v_lshlrev_b32_e32 v132, 16, v155
	v_add_f32_e32 v158, v134, v132
	v_and_b32_e32 v132, 0xffff0000, v155
	v_add_f32_e32 v159, v135, v132
	v_mul_f32_e32 v132, v157, v157
	v_fmac_f32_e32 v132, v156, v156
	v_fmac_f32_e32 v132, v158, v158
	v_fmac_f32_e32 v132, v159, v159
	s_nop 1
	v_mov_b32_dpp v133, v132 quad_perm:[1,0,3,2] row_mask:0xf bank_mask:0xf
	v_cvt_pk_bf16_f32 v156, v156, v157
	v_cvt_pk_bf16_f32 v157, v158, v159
	s_waitcnt lgkmcnt(0)
	v_add_f32_e32 v154, v132, v133
	s_nop 1
	v_mov_b32_dpp v155, v154 quad_perm:[2,3,0,1] row_mask:0xf bank_mask:0xf
	ds_read_b128 v[140:143], v199
	ds_read_b128 v[132:135], v202
	global_store_dwordx2 v[174:175], v[156:157], off offset:256
	s_waitcnt lgkmcnt(2)
	v_add_f32_e32 v154, v154, v155
	s_nop 1
	v_mov_b32_dpp v155, v154 row_half_mirror row_mask:0xf bank_mask:0xf
	s_and_saveexec_b64 s[6:7], vcc
	s_cbranch_execz .LBB0_476
	s_waitcnt lgkmcnt(0)
	v_add_f32_e32 v154, v154, v155
	global_atomic_add_f32 v[144:145], v154, off offset:640
; __device__ __forceinline__ float bflo(unsigned w) { return __uint_as_float(w << 16); }
; __device__ __forceinline__ float bfhi(unsigned w) { return __uint_as_float(w & 0xffff0000u); }
; template <int EPI> __device__ __forceinline__ void epi_res(const int tid_e, const GemmArgs& ga, int brow, int bcol, f32x4 (&acc)[2][2][4][2], char* epl) {
;     ...
;         f32x4 v[4];
; #pragma unroll
;         for (int i = 0; i < 4; ++i) { const int lrow = i * 8 + rr;
;           v[i] = *reinterpret_cast<const f32x4*>(sl + lrow * 128 + ((rc ^ ((lrow >> 1) & 7)) * 16)); }
; #pragma unroll
;         for (int i = 0; i < 4; ++i) {
;           const int row = brow + rl0 + ai * 128 + h * 32 + i * 8;
;           f32x4 x = v[i];
;           if (EPI == 3) x = x * scv;
;           if (EPI == 2) x = x + rf[h][i];
;           else { const u32x2 r = rb[bj][h][i]; x[0] += bflo(r[0]); x[1] += bfhi(r[0]); x[2] += bflo(r[1]); x[3] += bfhi(r[1]); }
;           if (EPI == 5) *reinterpret_cast<f32x4*>(ga.outf + (size_t)row * DM + col) = x;
;           else {
;             u32x2 w = {cvtpk(x[0], x[1]), cvtpk(x[2], x[3])};
;             *reinterpret_cast<u32x2*>(ga.Cb + (size_t)row * DM + col) = w;
;             float ss = x[0] * x[0] + x[1] * x[1] + x[2] * x[2] + x[3] * x[3];
;             ss += __shfl_xor(ss, 1); ss += __shfl_xor(ss, 2); ss += __shfl_xor(ss, 4);
;             if (rc == 0) atomicAdd(ga.rss_out + row, ss);
;           }
;         }
.LBB0_476:
	s_or_b64 exec, exec, s[6:7]
	v_lshlrev_b32_e32 v154, 16, v152
	s_waitcnt lgkmcnt(1)
	v_add_f32_e32 v154, v140, v154
	v_and_b32_e32 v140, 0xffff0000, v152
	v_add_f32_e32 v152, v141, v140
	v_lshlrev_b32_e32 v140, 16, v153
	s_waitcnt lgkmcnt(0)
	v_add_f32_e32 v155, v142, v140
	v_and_b32_e32 v140, 0xffff0000, v153
	v_add_f32_e32 v143, v143, v140
	v_mul_f32_e32 v140, v152, v152
	v_fmac_f32_e32 v140, v154, v154
	v_fmac_f32_e32 v140, v155, v155
	v_fmac_f32_e32 v140, v143, v143
	s_nop 1
	v_mov_b32_dpp v141, v140 quad_perm:[1,0,3,2] row_mask:0xf bank_mask:0xf
	v_cvt_pk_bf16_f32 v142, v154, v152
	v_cvt_pk_bf16_f32 v143, v155, v143
	global_store_dwordx2 v[176:177], v[142:143], off offset:256
	s_waitcnt lgkmcnt(0)
	v_add_f32_e32 v140, v140, v141
	s_nop 1
	v_mov_b32_dpp v141, v140 quad_perm:[2,3,0,1] row_mask:0xf bank_mask:0xf
	s_waitcnt lgkmcnt(0)
	v_add_f32_e32 v140, v140, v141
	s_nop 1
	v_mov_b32_dpp v141, v140 row_half_mirror row_mask:0xf bank_mask:0xf
	s_and_saveexec_b64 s[6:7], vcc
	s_cbranch_execz .LBB0_478
	s_waitcnt lgkmcnt(0)
	v_add_f32_e32 v140, v140, v141
	global_atomic_add_f32 v[144:145], v140, off offset:672
.LBB0_478:
	s_or_b64 exec, exec, s[6:7]
	s_waitcnt vmcnt(14)
	v_lshlrev_b32_e32 v140, 16, v148
	v_add_f32_e32 v140, v136, v140
	v_and_b32_e32 v136, 0xffff0000, v148
	s_waitcnt lgkmcnt(0)
	v_add_f32_e32 v141, v137, v136
	v_lshlrev_b32_e32 v136, 16, v149
	v_add_f32_e32 v142, v138, v136
	v_and_b32_e32 v136, 0xffff0000, v149
	v_add_f32_e32 v139, v139, v136
	v_mul_f32_e32 v136, v141, v141
	v_fmac_f32_e32 v136, v140, v140
	v_fmac_f32_e32 v136, v142, v142
	v_fmac_f32_e32 v136, v139, v139
	s_nop 1
	v_mov_b32_dpp v137, v136 quad_perm:[1,0,3,2] row_mask:0xf bank_mask:0xf
	v_cvt_pk_bf16_f32 v138, v140, v141
	v_cvt_pk_bf16_f32 v139, v142, v139
	global_store_dwordx2 v[178:179], v[138:139], off offset:256
	s_waitcnt lgkmcnt(0)
	v_add_f32_e32 v136, v136, v137
	s_nop 1
	v_mov_b32_dpp v137, v136 quad_perm:[2,3,0,1] row_mask:0xf bank_mask:0xf
	s_waitcnt lgkmcnt(0)
	v_add_f32_e32 v136, v136, v137
	s_nop 1
	v_mov_b32_dpp v137, v136 row_half_mirror row_mask:0xf bank_mask:0xf
	s_and_saveexec_b64 s[6:7], vcc
	s_cbranch_execz .LBB0_480
	s_waitcnt lgkmcnt(0)
	v_add_f32_e32 v136, v136, v137
	global_atomic_add_f32 v[144:145], v136, off offset:704
.LBB0_480:
	s_or_b64 exec, exec, s[6:7]
	v_lshlrev_b32_e32 v136, 16, v146
	v_add_f32_e32 v136, v132, v136
	v_and_b32_e32 v132, 0xffff0000, v146
	v_add_f32_e32 v133, v133, v132
	v_lshlrev_b32_e32 v132, 16, v147
	s_waitcnt lgkmcnt(0)
	v_add_f32_e32 v137, v134, v132
	v_and_b32_e32 v132, 0xffff0000, v147
	v_add_f32_e32 v135, v135, v132
	v_mul_f32_e32 v132, v133, v133
	v_fmac_f32_e32 v132, v136, v136
	v_fmac_f32_e32 v132, v137, v137
	v_fmac_f32_e32 v132, v135, v135
	s_nop 1
	v_mov_b32_dpp v96, v132 quad_perm:[1,0,3,2] row_mask:0xf bank_mask:0xf
	v_cvt_pk_bf16_f32 v134, v136, v133
	v_cvt_pk_bf16_f32 v135, v137, v135
	global_store_dwordx2 v[98:99], v[134:135], off offset:256
	s_waitcnt lgkmcnt(0)
	v_add_f32_e32 v96, v132, v96
	s_nop 1
	v_mov_b32_dpp v132, v96 quad_perm:[2,3,0,1] row_mask:0xf bank_mask:0xf
	s_waitcnt lgkmcnt(0)
	v_add_f32_e32 v96, v96, v132
	s_nop 1
	v_mov_b32_dpp v132, v96 row_half_mirror row_mask:0xf bank_mask:0xf
	s_and_saveexec_b64 s[6:7], vcc
	s_cbranch_execz .LBB0_482
	s_waitcnt lgkmcnt(0)
	v_add_f32_e32 v96, v96, v132
	global_atomic_add_f32 v[144:145], v96, off offset:736

; template <int EPI> __device__ __forceinline__ void epi_res(const int tid_e, const GemmArgs& ga, int brow, int bcol, f32x4 (&acc)[2][2][4][2], char* epl) {
;   const int wr_e = tid_e >> 8, wc_e = (tid_e >> 6) & 3, fr_e = tid_e & 15, fq_e = (tid_e >> 4) & 3, lane_e = tid_e & 63;
;   char* sl = epl + (tid_e >> 6) * 4096;
;   const int rr = lane_e >> 3, rc = lane_e & 7;
;   const float* resf = (brow < TP) ? ga.res0 + (size_t)brow * DM : ga.res1 + (size_t)(brow - TP) * DM;
;   const int rl0 = wr_e * 64 + rr, cl0 = bcol + wc_e * 32 + rc * 4;
;   u32x2 rb[2][2][4]; f32x4 rf[2][4];
; #pragma unroll
;   for (int ai = 0; ai < 2; ++ai) {
;     if (EPI != 2) {
; #pragma unroll
;       for (int bj = 0; bj < 2; ++bj)
; #pragma unroll
;         for (int h = 0; h < 2; ++h)
; #pragma unroll
;           for (int i = 0; i < 4; ++i)
;             rb[bj][h][i] = *reinterpret_cast<const u32x2*>(ga.resb + (size_t)(brow + rl0 + ai * 128 + h * 32 + i * 8) * DM + cl0 + bj * 128);
;     }
; #pragma unroll
;     for (int bj = 0; bj < 2; ++bj) {
;       const int col = cl0 + bj * 128;
;       f32x4 scv = {1.f, 1.f, 1.f, 1.f};
;       if (EPI == 3) scv = *reinterpret_cast<const f32x4*>(ga.scale + col);
;       if (EPI == 2) {
; #pragma unroll
;         for (int h = 0; h < 2; ++h)
; #pragma unroll
;           for (int i = 0; i < 4; ++i)
;             rf[h][i] = *reinterpret_cast<const f32x4*>(resf + (size_t)(rl0 + ai * 128 + h * 32 + i * 8) * DM + col);
;       }
; #pragma unroll
;       for (int h = 0; h < 2; ++h) {
; #pragma unroll
;         for (int mm = 0; mm < 2; ++mm) {
;           const int lrow = mm * 16 + fr_e;
; #pragma unroll
;           for (int n = 0; n < 2; ++n)
;             *reinterpret_cast<f32x4*>(sl + lrow * 128 + (((n * 4 + fq_e) ^ ((lrow >> 1) & 7)) * 16)) = acc[ai][bj][h * 2 + mm][n];
;         }
;         f32x4 v[4];
; #pragma unroll
;         for (int i = 0; i < 4; ++i) { const int lrow = i * 8 + rr;
;           v[i] = *reinterpret_cast<const f32x4*>(sl + lrow * 128 + ((rc ^ ((lrow >> 1) & 7)) * 16)); }
; #pragma unroll
;         for (int i = 0; i < 4; ++i) {
;           const int row = brow + rl0 + ai * 128 + h * 32 + i * 8;
;           f32x4 x = v[i];
;           if (EPI == 3) x = x * scv;
;           if (EPI == 2) x = x + rf[h][i];
.LBB0_484:
	s_and_b64 vcc, exec, s[6:7]
	s_cbranch_vccz .LBB0_560
	s_cmp_gt_i32 s53, 0
	s_cbranch_scc0 .LBB0_561
	s_cmp_gt_i32 s53, 2
	s_mov_b64 s[6:7], -1
	s_cbranch_scc0 .LBB0_562
	v_and_b32_e32 v231, 7, v226
	v_lshlrev_b32_e32 v99, 5, v227
	v_bfe_u32 v235, v226, 3, 3
	v_ashrrev_i32_e32 v98, 2, v226
	v_and_b32_e32 v99, 0x60, v99
	s_waitcnt lgkmcnt(0)
	v_lshlrev_b32_e32 v132, 2, v231
	v_and_or_b32 v98, v98, s33, v235
	v_or3_b32 v148, v99, v132, s16
	v_add_u32_e32 v98, s3, v98
	v_ashrrev_i32_e32 v149, 31, v148
	v_lshlrev_b64 v[180:181], 1, v[148:149]
	v_ashrrev_i32_e32 v99, 31, v98
	v_lshl_add_u64 v[154:155], s[94:95], 0, v[180:181]
	v_lshlrev_b64 v[156:157], 12, v[98:99]
	v_lshl_add_u64 v[152:153], v[148:149], 2, s[12:13]
	v_lshl_add_u64 v[136:137], v[154:155], 0, v[156:157]
	global_load_dwordx4 v[132:135], v[152:153], off
	global_load_dwordx2 v[144:145], v[136:137], off
	v_or_b32_e32 v138, 32, v98
	v_ashrrev_i32_e32 v139, 31, v138
	v_lshlrev_b64 v[188:189], 12, v[138:139]
	v_or_b32_e32 v138, 8, v98
	v_or_b32_e32 v158, 40, v98
	v_or_b32_e32 v160, 48, v98
	v_ashrrev_i32_e32 v139, 31, v138
	v_or_b32_e32 v140, 16, v98
	v_or_b32_e32 v142, 24, v98
	v_ashrrev_i32_e32 v159, 31, v158
	v_ashrrev_i32_e32 v161, 31, v160
	v_or_b32_e32 v162, 56, v98
	v_lshlrev_b64 v[182:183], 12, v[138:139]
	v_ashrrev_i32_e32 v141, 31, v140
	v_ashrrev_i32_e32 v143, 31, v142
	v_lshlrev_b64 v[190:191], 12, v[158:159]
	v_lshlrev_b64 v[178:179], 12, v[160:161]
	v_ashrrev_i32_e32 v163, 31, v162
	v_lshl_add_u64 v[138:139], v[154:155], 0, v[182:183]
	v_lshlrev_b64 v[184:185], 12, v[140:141]
	v_lshlrev_b64 v[186:187], 12, v[142:143]
	v_lshl_add_u64 v[158:159], v[154:155], 0, v[190:191]
	v_lshl_add_u64 v[160:161], v[154:155], 0, v[178:179]
	v_lshlrev_b64 v[174:175], 12, v[162:163]
	v_lshl_add_u64 v[140:141], v[154:155], 0, v[184:185]
	v_lshl_add_u64 v[142:143], v[154:155], 0, v[186:187]
	v_lshl_add_u64 v[146:147], v[154:155], 0, v[188:189]
	v_lshl_add_u64 v[228:229], v[154:155], 0, v[174:175]
	global_load_dwordx2 v[202:203], v[138:139], off
	global_load_dwordx2 v[170:171], v[138:139], off offset:256
	global_load_dwordx2 v[172:173], v[136:137], off offset:256
	global_load_dwordx2 v[200:201], v[140:141], off
	global_load_dwordx2 v[198:199], v[142:143], off
	global_load_dwordx2 v[166:167], v[142:143], off offset:256
	global_load_dwordx2 v[168:169], v[140:141], off offset:256
	global_load_dwordx2 v[196:197], v[146:147], off
	global_load_dwordx2 v[194:195], v[158:159], off
	global_load_dwordx2 v[162:163], v[158:159], off offset:256
	global_load_dwordx2 v[164:165], v[146:147], off offset:256
	global_load_dwordx2 v[192:193], v[160:161], off
	global_load_dwordx2 v[176:177], v[228:229], off
	s_nop 0
	global_load_dwordx2 v[158:159], v[228:229], off offset:256
	s_nop 0
	global_load_dwordx2 v[160:161], v[160:161], off offset:256
	v_lshrrev_b32_e32 v96, 4, v226
	s_add_i32 s6, 0, 0x20000
	v_lshlrev_b32_e32 v137, 7, v226
	v_bfe_u32 v138, v226, 1, 3
	v_lshl_add_u32 v234, v227, 12, s6
	v_lshrrev_b32_e32 v136, 3, v226
	v_and_b32_e32 v137, 0x780, v137
	v_bitop3_b32 v96, v96, v138, 3 bitop3:0x6c
	v_bfe_u32 v230, v226, 4, 2
	v_add_u32_e32 v137, v234, v137
	v_lshlrev_b32_e32 v96, 4, v96
	v_bfe_u32 v136, v136, 1, 2
	v_cmp_eq_u32_e32 vcc, 0, v231
	v_add_u32_e32 v231, v137, v96
	v_bitop3_b32 v96, v230, v138, 4 bitop3:0x36
	v_xor_b32_e32 v136, v136, v226
	v_lshlrev_b32_e32 v96, 4, v96
	v_lshlrev_b32_e32 v136, 4, v136
	v_add_u32_e32 v232, v137, v96
	v_lshl_add_u32 v96, v235, 7, v234
	v_and_b32_e32 v136, 0x70, v136
	v_add_u32_e32 v233, v96, v136
	v_or_b32_e32 v96, 8, v235
	v_lshl_add_u32 v136, v96, 7, v234
	v_lshrrev_b32_e32 v96, 1, v96
	v_xor_b32_e32 v96, v96, v226
	v_lshlrev_b32_e32 v96, 4, v96
	ds_write_b128 v231, v[128:131]
	ds_write_b128 v232, v[124:127]
	ds_write_b128 v231, v[120:123] offset:2048
	ds_write_b128 v232, v[116:119] offset:2048
	v_and_b32_e32 v96, 0x70, v96
	v_add_u32_e32 v230, v136, v96
	ds_read_b128 v[140:143], v233
	ds_read_b128 v[136:139], v233 offset:2048
	v_or_b32_e32 v96, 24, v235
	v_lshl_add_u32 v146, v96, 7, v234
	v_lshrrev_b32_e32 v147, 1, v96
	v_lshl_add_u64 v[98:99], v[98:99], 2, s[56:57]
	s_waitcnt vmcnt(16) lgkmcnt(1)
	v_pk_mul_f32 v[140:141], v[132:133], v[140:141]
	s_waitcnt vmcnt(15)
	v_lshlrev_b32_e32 v96, 16, v144
	v_add_f32_e32 v229, v140, v96
	v_and_b32_e32 v96, 0xffff0000, v144
	v_pk_mul_f32 v[142:143], v[134:135], v[142:143]
	v_add_f32_e32 v235, v141, v96
	v_lshlrev_b32_e32 v96, 16, v145
	v_add_f32_e32 v236, v142, v96
	v_and_b32_e32 v96, 0xffff0000, v145
	v_and_b32_e32 v141, 64, v212
	v_add_f32_e32 v237, v143, v96
	v_mul_f32_e32 v140, v235, v235
	v_xor_b32_e32 v96, 1, v212
	v_add_u32_e32 v240, 64, v141
	v_fmac_f32_e32 v140, v229, v229
	v_cmp_lt_i32_e64 s[6:7], v96, v240
	v_fmac_f32_e32 v140, v236, v236
	v_fmac_f32_e32 v140, v237, v237
	v_cndmask_b32_e64 v96, v212, v96, s[6:7]
	v_lshlrev_b32_e32 v96, 2, v96
	s_nop 1
	v_mov_b32_dpp v141, v140 quad_perm:[1,0,3,2] row_mask:0xf bank_mask:0xf
	v_cvt_pk_bf16_f32 v238, v229, v235
	v_xor_b32_e32 v229, 4, v212
	v_xor_b32_e32 v142, v147, v226
	v_lshlrev_b32_e32 v142, 4, v142
	s_waitcnt lgkmcnt(0)
	v_add_f32_e32 v241, v140, v141
	v_xor_b32_e32 v140, 2, v212
	v_cmp_lt_i32_e64 s[6:7], v140, v240
	v_and_b32_e32 v142, 0x70, v142
	v_add_u32_e32 v234, v146, v142
	v_cndmask_b32_e64 v140, v212, v140, s[6:7]
	v_lshlrev_b32_e32 v228, 2, v140
	s_nop 1
	v_mov_b32_dpp v242, v241 quad_perm:[2,3,0,1] row_mask:0xf bank_mask:0xf
	v_cmp_lt_i32_e64 s[6:7], v229, v240
	ds_read_b128 v[144:147], v230
	ds_read_b128 v[140:143], v234
	v_cndmask_b32_e64 v229, v212, v229, s[6:7]
	v_lshlrev_b32_e32 v229, 2, v229
	s_waitcnt lgkmcnt(2)
	v_add_f32_e32 v235, v241, v242
	v_cvt_pk_bf16_f32 v239, v236, v237
	s_nop 1
	v_mov_b32_dpp v236, v235 row_half_mirror row_mask:0xf bank_mask:0xf
	v_lshl_add_u64 v[240:241], s[96:97], 0, v[156:157]
	v_lshl_add_u64 v[180:181], v[240:241], 0, v[180:181]
	global_store_dwordx2 v[180:181], v[238:239], off
	s_and_saveexec_b64 s[6:7], vcc
	s_cbranch_execz .LBB0_489
	s_waitcnt lgkmcnt(0)
	v_add_f32_e32 v235, v235, v236
	global_atomic_add_f32 v[98:99], v235, off
; __device__ __forceinline__ float bflo(unsigned w) { return __uint_as_float(w << 16); }
; __device__ __forceinline__ float bfhi(unsigned w) { return __uint_as_float(w & 0xffff0000u); }
; template <int EPI> __device__ __forceinline__ void epi_res(const int tid_e, const GemmArgs& ga, int brow, int bcol, f32x4 (&acc)[2][2][4][2], char* epl) {
;     ...
;     for (int bj = 0; bj < 2; ++bj) {
;       const int col = cl0 + bj * 128;
;       f32x4 scv = {1.f, 1.f, 1.f, 1.f};
;       if (EPI == 3) scv = *reinterpret_cast<const f32x4*>(ga.scale + col);
;       if (EPI == 2) {
; #pragma unroll
;         for (int h = 0; h < 2; ++h)
; #pragma unroll
;           for (int i = 0; i < 4; ++i)
;             rf[h][i] = *reinterpret_cast<const f32x4*>(resf + (size_t)(rl0 + ai * 128 + h * 32 + i * 8) * DM + col);
;       }
; #pragma unroll
;       for (int h = 0; h < 2; ++h) {
; #pragma unroll
;         for (int mm = 0; mm < 2; ++mm) {
;           const int lrow = mm * 16 + fr_e;
; #pragma unroll
;           for (int n = 0; n < 2; ++n)
;             *reinterpret_cast<f32x4*>(sl + lrow * 128 + (((n * 4 + fq_e) ^ ((lrow >> 1) & 7)) * 16)) = acc[ai][bj][h * 2 + mm][n];
;         }
;         f32x4 v[4];
; #pragma unroll
;         for (int i = 0; i < 4; ++i) { const int lrow = i * 8 + rr;
;           v[i] = *reinterpret_cast<const f32x4*>(sl + lrow * 128 + ((rc ^ ((lrow >> 1) & 7)) * 16)); }
; #pragma unroll
;         for (int i = 0; i < 4; ++i) {
;           const int row = brow + rl0 + ai * 128 + h * 32 + i * 8;
;           f32x4 x = v[i];
;           if (EPI == 3) x = x * scv;
;           if (EPI == 2) x = x + rf[h][i];
;           else { const u32x2 r = rb[bj][h][i]; x[0] += bflo(r[0]); x[1] += bfhi(r[0]); x[2] += bflo(r[1]); x[3] += bfhi(r[1]); }
;           if (EPI == 5) *reinterpret_cast<f32x4*>(ga.outf + (size_t)row * DM + col) = x;
;           else {
;             u32x2 w = {cvtpk(x[0], x[1]), cvtpk(x[2], x[3])};
;             *reinterpret_cast<u32x2*>(ga.Cb + (size_t)row * DM + col) = w;
;             float ss = x[0] * x[0] + x[1] * x[1] + x[2] * x[2] + x[3] * x[3];
;             ss += __shfl_xor(ss, 1); ss += __shfl_xor(ss, 2); ss += __shfl_xor(ss, 4);
;             if (rc == 0) atomicAdd(ga.rss_out + row, ss);
;           }
;         }
.LBB0_489:
	s_or_b64 exec, exec, s[6:7]
	s_waitcnt lgkmcnt(1)
	v_pk_mul_f32 v[144:145], v[132:133], v[144:145]
	s_waitcnt vmcnt(15)
	v_lshlrev_b32_e32 v235, 16, v202
	v_and_b32_e32 v202, 0xffff0000, v202
	v_pk_mul_f32 v[146:147], v[134:135], v[146:147]
	v_add_f32_e32 v145, v145, v202
	v_lshlrev_b32_e32 v202, 16, v203
	v_add_f32_e32 v202, v146, v202
	v_and_b32_e32 v146, 0xffff0000, v203
	v_add_f32_e32 v144, v144, v235
	v_add_f32_e32 v147, v147, v146
	v_mul_f32_e32 v146, v145, v145
	v_fmac_f32_e32 v146, v144, v144
	v_fmac_f32_e32 v146, v202, v202
	v_fmac_f32_e32 v146, v147, v147
	s_nop 1
	v_mov_b32_dpp v203, v146 quad_perm:[1,0,3,2] row_mask:0xf bank_mask:0xf
	v_lshl_add_u64 v[182:183], s[96:97], 0, v[182:183]
	v_lshl_add_u64 v[182:183], v[148:149], 1, v[182:183]
	v_cvt_pk_bf16_f32 v147, v202, v147
	s_waitcnt lgkmcnt(0)
	v_add_f32_e32 v203, v146, v203
	s_nop 1
	v_mov_b32_dpp v235, v203 quad_perm:[2,3,0,1] row_mask:0xf bank_mask:0xf
	v_cvt_pk_bf16_f32 v146, v144, v145
	global_store_dwordx2 v[182:183], v[146:147], off
	s_waitcnt lgkmcnt(0)
	v_add_f32_e32 v144, v203, v235
	s_nop 1
	v_mov_b32_dpp v145, v144 row_half_mirror row_mask:0xf bank_mask:0xf
	s_and_saveexec_b64 s[6:7], vcc
	s_cbranch_execz .LBB0_491
	s_waitcnt lgkmcnt(0)
	v_add_f32_e32 v144, v144, v145
	global_atomic_add_f32 v[98:99], v144, off offset:32
.LBB0_491:
	s_or_b64 exec, exec, s[6:7]
	v_pk_mul_f32 v[136:137], v[132:133], v[136:137]
	s_waitcnt vmcnt(13)
	v_lshlrev_b32_e32 v144, 16, v200
	v_add_f32_e32 v136, v136, v144
	v_and_b32_e32 v144, 0xffff0000, v200
	v_pk_mul_f32 v[138:139], v[134:135], v[138:139]
	v_add_f32_e32 v137, v137, v144
	v_lshlrev_b32_e32 v144, 16, v201
	v_add_f32_e32 v144, v138, v144
	v_and_b32_e32 v138, 0xffff0000, v201
	v_add_f32_e32 v139, v139, v138
	v_mul_f32_e32 v138, v137, v137
	v_fmac_f32_e32 v138, v136, v136
	v_fmac_f32_e32 v138, v144, v144
	v_fmac_f32_e32 v138, v139, v139
	s_waitcnt lgkmcnt(0)
	s_nop 1
	v_mov_b32_dpp v145, v138 quad_perm:[1,0,3,2] row_mask:0xf bank_mask:0xf
	v_cvt_pk_bf16_f32 v139, v144, v139
	s_waitcnt lgkmcnt(0)
	v_add_f32_e32 v145, v138, v145
	s_nop 1
	v_mov_b32_dpp v146, v145 quad_perm:[2,3,0,1] row_mask:0xf bank_mask:0xf
	v_cvt_pk_bf16_f32 v138, v136, v137
	s_waitcnt lgkmcnt(0)
	v_add_f32_e32 v136, v145, v146
	s_nop 1
	v_mov_b32_dpp v137, v136 row_half_mirror row_mask:0xf bank_mask:0xf
	v_lshl_add_u64 v[144:145], s[96:97], 0, v[184:185]
	v_lshl_add_u64 v[184:185], v[148:149], 1, v[144:145]
	global_store_dwordx2 v[184:185], v[138:139], off
	s_and_saveexec_b64 s[6:7], vcc
	s_cbranch_execz .LBB0_493
	s_waitcnt lgkmcnt(0)
	v_add_f32_e32 v136, v136, v137
	global_atomic_add_f32 v[98:99], v136, off offset:64
.LBB0_493:
	s_or_b64 exec, exec, s[6:7]
	v_pk_mul_f32 v[138:139], v[132:133], v[140:141]
	s_waitcnt vmcnt(13)
	v_lshlrev_b32_e32 v140, 16, v198
	v_add_f32_e32 v138, v138, v140
	v_and_b32_e32 v140, 0xffff0000, v198
	s_waitcnt lgkmcnt(0)
	v_pk_mul_f32 v[136:137], v[134:135], v[142:143]
	v_add_f32_e32 v139, v139, v140
	v_lshlrev_b32_e32 v140, 16, v199
	v_add_f32_e32 v140, v136, v140
	v_and_b32_e32 v136, 0xffff0000, v199
	v_add_f32_e32 v141, v137, v136
	v_mul_f32_e32 v136, v139, v139
	v_fmac_f32_e32 v136, v138, v138
	v_fmac_f32_e32 v136, v140, v140
	v_fmac_f32_e32 v136, v141, v141
	s_nop 1
	v_mov_b32_dpp v137, v136 quad_perm:[1,0,3,2] row_mask:0xf bank_mask:0xf
	v_cvt_pk_bf16_f32 v138, v138, v139
	v_cvt_pk_bf16_f32 v139, v140, v141
	v_lshl_add_u64 v[140:141], s[96:97], 0, v[186:187]
	v_lshl_add_u64 v[186:187], v[148:149], 1, v[140:141]
	s_waitcnt lgkmcnt(0)
	v_add_f32_e32 v136, v136, v137
	s_nop 1
	v_mov_b32_dpp v137, v136 quad_perm:[2,3,0,1] row_mask:0xf bank_mask:0xf
	global_store_dwordx2 v[186:187], v[138:139], off
	s_waitcnt lgkmcnt(0)
	v_add_f32_e32 v136, v136, v137
	s_nop 1
	v_mov_b32_dpp v137, v136 row_half_mirror row_mask:0xf bank_mask:0xf
	s_and_saveexec_b64 s[6:7], vcc
	s_cbranch_execz .LBB0_495
	s_waitcnt lgkmcnt(0)
	v_add_f32_e32 v136, v136, v137
	global_atomic_add_f32 v[98:99], v136, off offset:96
.LBB0_495:
	s_or_b64 exec, exec, s[6:7]
	ds_write_b128 v231, v[112:115]
	ds_write_b128 v232, v[108:111]
	ds_read_b128 v[140:143], v233
	s_waitcnt vmcnt(11)
	v_lshlrev_b32_e32 v144, 16, v196
	ds_write_b128 v231, v[104:107] offset:2048
	ds_write_b128 v232, v[100:103] offset:2048
	s_waitcnt lgkmcnt(5)
	ds_read_b128 v[136:139], v233 offset:2048
	v_lshl_add_u64 v[188:189], s[96:97], 0, v[188:189]
	s_waitcnt lgkmcnt(3)
	v_pk_mul_f32 v[140:141], v[132:133], v[140:141]
	v_pk_mul_f32 v[142:143], v[134:135], v[142:143]
	v_add_f32_e32 v198, v140, v144
	v_and_b32_e32 v140, 0xffff0000, v196
	v_add_f32_e32 v196, v141, v140
	v_lshlrev_b32_e32 v140, 16, v197
	v_add_f32_e32 v199, v142, v140
	v_and_b32_e32 v140, 0xffff0000, v197
	v_add_f32_e32 v200, v143, v140
	v_mul_f32_e32 v140, v196, v196
	v_fmac_f32_e32 v140, v198, v198
	v_fmac_f32_e32 v140, v199, v199
	v_fmac_f32_e32 v140, v200, v200
	s_nop 1
	v_mov_b32_dpp v141, v140 quad_perm:[1,0,3,2] row_mask:0xf bank_mask:0xf
	v_cvt_pk_bf16_f32 v198, v198, v196
	v_lshl_add_u64 v[188:189], v[148:149], 1, v[188:189]
	v_cvt_pk_bf16_f32 v199, v199, v200
	s_waitcnt lgkmcnt(0)
	v_add_f32_e32 v197, v140, v141
	s_nop 1
	v_mov_b32_dpp v201, v197 quad_perm:[2,3,0,1] row_mask:0xf bank_mask:0xf
	ds_read_b128 v[144:147], v230
	ds_read_b128 v[140:143], v234
	global_store_dwordx2 v[188:189], v[198:199], off
	s_waitcnt lgkmcnt(2)
	v_add_f32_e32 v196, v197, v201
	s_nop 1
	v_mov_b32_dpp v197, v196 row_half_mirror row_mask:0xf bank_mask:0xf
	s_and_saveexec_b64 s[6:7], vcc
	s_cbranch_execz .LBB0_497
	s_waitcnt lgkmcnt(0)
	v_add_f32_e32 v196, v196, v197
	global_atomic_add_f32 v[98:99], v196, off offset:128
; __device__ __forceinline__ float bflo(unsigned w) { return __uint_as_float(w << 16); }
; __device__ __forceinline__ float bfhi(unsigned w) { return __uint_as_float(w & 0xffff0000u); }
; template <int EPI> __device__ __forceinline__ void epi_res(const int tid_e, const GemmArgs& ga, int brow, int bcol, f32x4 (&acc)[2][2][4][2], char* epl) {
;     ...
;     for (int bj = 0; bj < 2; ++bj) {
;       const int col = cl0 + bj * 128;
;       f32x4 scv = {1.f, 1.f, 1.f, 1.f};
;       if (EPI == 3) scv = *reinterpret_cast<const f32x4*>(ga.scale + col);
;       if (EPI == 2) {
; #pragma unroll
;         for (int h = 0; h < 2; ++h)
; #pragma unroll
;           for (int i = 0; i < 4; ++i)
;             rf[h][i] = *reinterpret_cast<const f32x4*>(resf + (size_t)(rl0 + ai * 128 + h * 32 + i * 8) * DM + col);
;       }
; #pragma unroll
;       for (int h = 0; h < 2; ++h) {
; #pragma unroll
;         for (int mm = 0; mm < 2; ++mm) {
;           const int lrow = mm * 16 + fr_e;
; #pragma unroll
;           for (int n = 0; n < 2; ++n)
;             *reinterpret_cast<f32x4*>(sl + lrow * 128 + (((n * 4 + fq_e) ^ ((lrow >> 1) & 7)) * 16)) = acc[ai][bj][h * 2 + mm][n];
;         }
;         f32x4 v[4];
; #pragma unroll
;         for (int i = 0; i < 4; ++i) { const int lrow = i * 8 + rr;
;           v[i] = *reinterpret_cast<const f32x4*>(sl + lrow * 128 + ((rc ^ ((lrow >> 1) & 7)) * 16)); }
; #pragma unroll
;         for (int i = 0; i < 4; ++i) {
;           const int row = brow + rl0 + ai * 128 + h * 32 + i * 8;
;           f32x4 x = v[i];
;           if (EPI == 3) x = x * scv;
;           if (EPI == 2) x = x + rf[h][i];
;           else { const u32x2 r = rb[bj][h][i]; x[0] += bflo(r[0]); x[1] += bfhi(r[0]); x[2] += bflo(r[1]); x[3] += bfhi(r[1]); }
;           if (EPI == 5) *reinterpret_cast<f32x4*>(ga.outf + (size_t)row * DM + col) = x;
;           else {
;             u32x2 w = {cvtpk(x[0], x[1]), cvtpk(x[2], x[3])};
;             *reinterpret_cast<u32x2*>(ga.Cb + (size_t)row * DM + col) = w;
;             float ss = x[0] * x[0] + x[1] * x[1] + x[2] * x[2] + x[3] * x[3];
;             ss += __shfl_xor(ss, 1); ss += __shfl_xor(ss, 2); ss += __shfl_xor(ss, 4);
;             if (rc == 0) atomicAdd(ga.rss_out + row, ss);
;           }
;         }
.LBB0_497:
	s_or_b64 exec, exec, s[6:7]
	s_waitcnt lgkmcnt(1)
	v_pk_mul_f32 v[144:145], v[132:133], v[144:145]
	s_waitcnt vmcnt(11)
	v_lshlrev_b32_e32 v196, 16, v194
	v_and_b32_e32 v194, 0xffff0000, v194
	v_pk_mul_f32 v[146:147], v[134:135], v[146:147]
	v_add_f32_e32 v145, v145, v194
	v_lshlrev_b32_e32 v194, 16, v195
	v_add_f32_e32 v194, v146, v194
	v_and_b32_e32 v146, 0xffff0000, v195
	v_add_f32_e32 v144, v144, v196
	v_add_f32_e32 v147, v147, v146
	v_mul_f32_e32 v146, v145, v145
	v_fmac_f32_e32 v146, v144, v144
	v_fmac_f32_e32 v146, v194, v194
	v_fmac_f32_e32 v146, v147, v147
	s_nop 1
	v_mov_b32_dpp v195, v146 quad_perm:[1,0,3,2] row_mask:0xf bank_mask:0xf
	v_lshl_add_u64 v[190:191], s[96:97], 0, v[190:191]
	v_lshl_add_u64 v[190:191], v[148:149], 1, v[190:191]
	v_cvt_pk_bf16_f32 v147, v194, v147
	s_waitcnt lgkmcnt(0)
	v_add_f32_e32 v195, v146, v195
	s_nop 1
	v_mov_b32_dpp v196, v195 quad_perm:[2,3,0,1] row_mask:0xf bank_mask:0xf
	v_cvt_pk_bf16_f32 v146, v144, v145
	global_store_dwordx2 v[190:191], v[146:147], off
	s_waitcnt lgkmcnt(0)
	v_add_f32_e32 v144, v195, v196
	s_nop 1
	v_mov_b32_dpp v145, v144 row_half_mirror row_mask:0xf bank_mask:0xf
	s_and_saveexec_b64 s[6:7], vcc
	s_cbranch_execz .LBB0_499
	s_waitcnt lgkmcnt(0)
	v_add_f32_e32 v144, v144, v145
	global_atomic_add_f32 v[98:99], v144, off offset:160
.LBB0_499:
	s_or_b64 exec, exec, s[6:7]
	v_pk_mul_f32 v[136:137], v[132:133], v[136:137]
	s_waitcnt vmcnt(9)
	v_lshlrev_b32_e32 v144, 16, v192
	v_add_f32_e32 v136, v136, v144
	v_and_b32_e32 v144, 0xffff0000, v192
	v_pk_mul_f32 v[138:139], v[134:135], v[138:139]
	v_add_f32_e32 v137, v137, v144
	v_lshlrev_b32_e32 v144, 16, v193
	v_add_f32_e32 v144, v138, v144
	v_and_b32_e32 v138, 0xffff0000, v193
	v_add_f32_e32 v139, v139, v138
	v_mul_f32_e32 v138, v137, v137
	v_fmac_f32_e32 v138, v136, v136
	v_fmac_f32_e32 v138, v144, v144
	v_fmac_f32_e32 v138, v139, v139
	s_waitcnt lgkmcnt(0)
	s_nop 1
	v_mov_b32_dpp v145, v138 quad_perm:[1,0,3,2] row_mask:0xf bank_mask:0xf
	v_cvt_pk_bf16_f32 v139, v144, v139
	s_waitcnt lgkmcnt(0)
	v_add_f32_e32 v145, v138, v145
	s_nop 1
	v_mov_b32_dpp v146, v145 quad_perm:[2,3,0,1] row_mask:0xf bank_mask:0xf
	v_cvt_pk_bf16_f32 v138, v136, v137
	s_waitcnt lgkmcnt(0)
	v_add_f32_e32 v136, v145, v146
	s_nop 1
	v_mov_b32_dpp v137, v136 row_half_mirror row_mask:0xf bank_mask:0xf
	v_lshl_add_u64 v[144:145], s[96:97], 0, v[178:179]
	v_lshl_add_u64 v[178:179], v[148:149], 1, v[144:145]
	global_store_dwordx2 v[178:179], v[138:139], off
	s_and_saveexec_b64 s[6:7], vcc
	s_cbranch_execz .LBB0_501
	s_waitcnt lgkmcnt(0)
	v_add_f32_e32 v136, v136, v137
	global_atomic_add_f32 v[98:99], v136, off offset:192
.LBB0_501:
	s_or_b64 exec, exec, s[6:7]
	v_pk_mul_f32 v[132:133], v[132:133], v[140:141]
	s_waitcnt vmcnt(9)
	v_lshlrev_b32_e32 v136, 16, v176
	v_add_f32_e32 v132, v132, v136
	v_and_b32_e32 v136, 0xffff0000, v176
	v_pk_mul_f32 v[134:135], v[134:135], v[142:143]
	v_add_f32_e32 v133, v133, v136
	v_lshlrev_b32_e32 v136, 16, v177
	v_add_f32_e32 v136, v134, v136
	v_and_b32_e32 v134, 0xffff0000, v177
	v_add_f32_e32 v135, v135, v134
	v_mul_f32_e32 v134, v133, v133
	v_fmac_f32_e32 v134, v132, v132
	v_fmac_f32_e32 v134, v136, v136
	v_fmac_f32_e32 v134, v135, v135
	s_waitcnt lgkmcnt(0)
	s_nop 1
	v_mov_b32_dpp v137, v134 quad_perm:[1,0,3,2] row_mask:0xf bank_mask:0xf
	v_cvt_pk_bf16_f32 v135, v136, v135
	s_waitcnt lgkmcnt(0)
	v_add_f32_e32 v137, v134, v137
	s_nop 1
	v_mov_b32_dpp v138, v137 quad_perm:[2,3,0,1] row_mask:0xf bank_mask:0xf
	v_cvt_pk_bf16_f32 v134, v132, v133
	s_waitcnt lgkmcnt(0)
	v_add_f32_e32 v132, v137, v138
	s_nop 1
	v_mov_b32_dpp v133, v132 row_half_mirror row_mask:0xf bank_mask:0xf
	v_lshl_add_u64 v[136:137], s[96:97], 0, v[174:175]
	v_lshl_add_u64 v[174:175], v[148:149], 1, v[136:137]
	global_store_dwordx2 v[174:175], v[134:135], off
	s_and_saveexec_b64 s[6:7], vcc
	s_cbranch_execz .LBB0_503
	s_waitcnt lgkmcnt(0)
	v_add_f32_e32 v132, v132, v133
	global_atomic_add_f32 v[98:99], v132, off offset:224
.LBB0_503:
	s_or_b64 exec, exec, s[6:7]
	s_waitcnt lgkmcnt(0)
	global_load_dwordx4 v[132:135], v[152:153], off offset:512
	ds_write_b128 v231, v[92:95]
	ds_write_b128 v232, v[88:91]
	ds_write_b128 v231, v[84:87] offset:2048
	ds_write_b128 v232, v[80:83] offset:2048
	ds_read_b128 v[136:139], v233
	ds_read_b128 v[140:143], v233 offset:2048
	v_and_b32_e32 v145, 0xffff0000, v172
	v_lshlrev_b32_e32 v144, 16, v172
	v_lshlrev_b32_e32 v146, 16, v173
	v_and_b32_e32 v147, 0xffff0000, v173
	s_waitcnt vmcnt(0) lgkmcnt(1)
	v_pk_mul_f32 v[136:137], v[132:133], v[136:137]
	s_nop 0
	v_add_f32_e32 v177, v137, v145
	v_pk_mul_f32 v[138:139], v[134:135], v[138:139]
	v_add_f32_e32 v176, v136, v144
	v_mul_f32_e32 v136, v177, v177
	v_add_f32_e32 v192, v138, v146
	v_fmac_f32_e32 v136, v176, v176
	v_add_f32_e32 v193, v139, v147
	v_fmac_f32_e32 v136, v192, v192
	v_fmac_f32_e32 v136, v193, v193
	s_nop 1
	v_mov_b32_dpp v137, v136 quad_perm:[1,0,3,2] row_mask:0xf bank_mask:0xf
	v_cvt_pk_bf16_f32 v176, v176, v177
	v_cvt_pk_bf16_f32 v177, v192, v193
	s_waitcnt lgkmcnt(0)
	v_add_f32_e32 v172, v136, v137
	s_nop 1
	v_mov_b32_dpp v173, v172 quad_perm:[2,3,0,1] row_mask:0xf bank_mask:0xf
	ds_read_b128 v[144:147], v230
	ds_read_b128 v[136:139], v234
	global_store_dwordx2 v[180:181], v[176:177], off offset:256
	s_waitcnt lgkmcnt(2)
	v_add_f32_e32 v172, v172, v173
	s_nop 1
	v_mov_b32_dpp v173, v172 row_half_mirror row_mask:0xf bank_mask:0xf
	s_and_saveexec_b64 s[6:7], vcc
	s_cbranch_execz .LBB0_505
	s_waitcnt lgkmcnt(0)
	v_add_f32_e32 v172, v172, v173
	global_atomic_add_f32 v[98:99], v172, off
; __device__ __forceinline__ float bflo(unsigned w) { return __uint_as_float(w << 16); }
; __device__ __forceinline__ float bfhi(unsigned w) { return __uint_as_float(w & 0xffff0000u); }
; template <int EPI> __device__ __forceinline__ void epi_res(const int tid_e, const GemmArgs& ga, int brow, int bcol, f32x4 (&acc)[2][2][4][2], char* epl) {
;     ...
;     for (int bj = 0; bj < 2; ++bj) {
;       const int col = cl0 + bj * 128;
;       f32x4 scv = {1.f, 1.f, 1.f, 1.f};
;       if (EPI == 3) scv = *reinterpret_cast<const f32x4*>(ga.scale + col);
;       if (EPI == 2) {
; #pragma unroll
;         for (int h = 0; h < 2; ++h)
; #pragma unroll
;           for (int i = 0; i < 4; ++i)
;             rf[h][i] = *reinterpret_cast<const f32x4*>(resf + (size_t)(rl0 + ai * 128 + h * 32 + i * 8) * DM + col);
;       }
; #pragma unroll
;       for (int h = 0; h < 2; ++h) {
; #pragma unroll
;         for (int mm = 0; mm < 2; ++mm) {
;           const int lrow = mm * 16 + fr_e;
; #pragma unroll
;           for (int n = 0; n < 2; ++n)
;             *reinterpret_cast<f32x4*>(sl + lrow * 128 + (((n * 4 + fq_e) ^ ((lrow >> 1) & 7)) * 16)) = acc[ai][bj][h * 2 + mm][n];
;         }
;         f32x4 v[4];
; #pragma unroll
;         for (int i = 0; i < 4; ++i) { const int lrow = i * 8 + rr;
;           v[i] = *reinterpret_cast<const f32x4*>(sl + lrow * 128 + ((rc ^ ((lrow >> 1) & 7)) * 16)); }
; #pragma unroll
;         for (int i = 0; i < 4; ++i) {
;           const int row = brow + rl0 + ai * 128 + h * 32 + i * 8;
;           f32x4 x = v[i];
;           if (EPI == 3) x = x * scv;
;           if (EPI == 2) x = x + rf[h][i];
;           else { const u32x2 r = rb[bj][h][i]; x[0] += bflo(r[0]); x[1] += bfhi(r[0]); x[2] += bflo(r[1]); x[3] += bfhi(r[1]); }
;           if (EPI == 5) *reinterpret_cast<f32x4*>(ga.outf + (size_t)row * DM + col) = x;
;           else {
;             u32x2 w = {cvtpk(x[0], x[1]), cvtpk(x[2], x[3])};
;             *reinterpret_cast<u32x2*>(ga.Cb + (size_t)row * DM + col) = w;
;             float ss = x[0] * x[0] + x[1] * x[1] + x[2] * x[2] + x[3] * x[3];
;             ss += __shfl_xor(ss, 1); ss += __shfl_xor(ss, 2); ss += __shfl_xor(ss, 4);
;             if (rc == 0) atomicAdd(ga.rss_out + row, ss);
;           }
;         }
.LBB0_505:
	s_or_b64 exec, exec, s[6:7]
	s_waitcnt lgkmcnt(1)
	v_pk_mul_f32 v[144:145], v[132:133], v[144:145]
	v_lshlrev_b32_e32 v172, 16, v170
	v_add_f32_e32 v172, v144, v172
	v_and_b32_e32 v144, 0xffff0000, v170
	v_pk_mul_f32 v[146:147], v[134:135], v[146:147]
	v_add_f32_e32 v170, v145, v144
	v_lshlrev_b32_e32 v144, 16, v171
	s_waitcnt lgkmcnt(0)
	v_add_f32_e32 v173, v146, v144
	v_and_b32_e32 v144, 0xffff0000, v171
	v_add_f32_e32 v147, v147, v144
	v_mul_f32_e32 v144, v170, v170
	v_fmac_f32_e32 v144, v172, v172
	v_fmac_f32_e32 v144, v173, v173
	v_fmac_f32_e32 v144, v147, v147
	s_nop 1
	v_mov_b32_dpp v145, v144 quad_perm:[1,0,3,2] row_mask:0xf bank_mask:0xf
	v_cvt_pk_bf16_f32 v146, v172, v170
	v_cvt_pk_bf16_f32 v147, v173, v147
	global_store_dwordx2 v[182:183], v[146:147], off offset:256
	s_waitcnt lgkmcnt(0)
	v_add_f32_e32 v144, v144, v145
	s_nop 1
	v_mov_b32_dpp v145, v144 quad_perm:[2,3,0,1] row_mask:0xf bank_mask:0xf
	s_waitcnt lgkmcnt(0)
	v_add_f32_e32 v144, v144, v145
	s_nop 1
	v_mov_b32_dpp v145, v144 row_half_mirror row_mask:0xf bank_mask:0xf
	s_and_saveexec_b64 s[6:7], vcc
	s_cbranch_execz .LBB0_507
	s_waitcnt lgkmcnt(0)
	v_add_f32_e32 v144, v144, v145
	global_atomic_add_f32 v[98:99], v144, off offset:32
.LBB0_507:
	s_or_b64 exec, exec, s[6:7]
	v_pk_mul_f32 v[140:141], v[132:133], v[140:141]
	v_lshlrev_b32_e32 v144, 16, v168
	v_add_f32_e32 v144, v140, v144
	v_and_b32_e32 v140, 0xffff0000, v168
	v_pk_mul_f32 v[142:143], v[134:135], v[142:143]
	s_waitcnt lgkmcnt(0)
	v_add_f32_e32 v145, v141, v140
	v_lshlrev_b32_e32 v140, 16, v169
	v_add_f32_e32 v146, v142, v140
	v_and_b32_e32 v140, 0xffff0000, v169
	v_add_f32_e32 v143, v143, v140
	v_mul_f32_e32 v140, v145, v145
	v_fmac_f32_e32 v140, v144, v144
	v_fmac_f32_e32 v140, v146, v146
	v_fmac_f32_e32 v140, v143, v143
	s_nop 1
	v_mov_b32_dpp v141, v140 quad_perm:[1,0,3,2] row_mask:0xf bank_mask:0xf
	v_cvt_pk_bf16_f32 v142, v144, v145
	v_cvt_pk_bf16_f32 v143, v146, v143
	global_store_dwordx2 v[184:185], v[142:143], off offset:256
	s_waitcnt lgkmcnt(0)
	v_add_f32_e32 v140, v140, v141
	s_nop 1
	v_mov_b32_dpp v141, v140 quad_perm:[2,3,0,1] row_mask:0xf bank_mask:0xf
	s_waitcnt lgkmcnt(0)
	v_add_f32_e32 v140, v140, v141
	s_nop 1
	v_mov_b32_dpp v141, v140 row_half_mirror row_mask:0xf bank_mask:0xf
	s_and_saveexec_b64 s[6:7], vcc
	s_cbranch_execz .LBB0_509
	s_waitcnt lgkmcnt(0)
	v_add_f32_e32 v140, v140, v141
	global_atomic_add_f32 v[98:99], v140, off offset:64
.LBB0_509:
	s_or_b64 exec, exec, s[6:7]
	v_pk_mul_f32 v[136:137], v[132:133], v[136:137]
	v_lshlrev_b32_e32 v140, 16, v166
	v_add_f32_e32 v140, v136, v140
	v_and_b32_e32 v136, 0xffff0000, v166
	v_pk_mul_f32 v[138:139], v[134:135], v[138:139]
	s_waitcnt lgkmcnt(0)
	v_add_f32_e32 v141, v137, v136
	v_lshlrev_b32_e32 v136, 16, v167
	v_add_f32_e32 v142, v138, v136
	v_and_b32_e32 v136, 0xffff0000, v167
	v_add_f32_e32 v139, v139, v136
	v_mul_f32_e32 v136, v141, v141
	v_fmac_f32_e32 v136, v140, v140
	v_fmac_f32_e32 v136, v142, v142
	v_fmac_f32_e32 v136, v139, v139
	s_nop 1
	v_mov_b32_dpp v137, v136 quad_perm:[1,0,3,2] row_mask:0xf bank_mask:0xf
	v_cvt_pk_bf16_f32 v138, v140, v141
	v_cvt_pk_bf16_f32 v139, v142, v139
	global_store_dwordx2 v[186:187], v[138:139], off offset:256
	s_waitcnt lgkmcnt(0)
	v_add_f32_e32 v136, v136, v137
	s_nop 1
	v_mov_b32_dpp v137, v136 quad_perm:[2,3,0,1] row_mask:0xf bank_mask:0xf
	s_waitcnt lgkmcnt(0)
	v_add_f32_e32 v136, v136, v137
	s_nop 1
	v_mov_b32_dpp v137, v136 row_half_mirror row_mask:0xf bank_mask:0xf
	s_and_saveexec_b64 s[6:7], vcc
	s_cbranch_execz .LBB0_511
	s_waitcnt lgkmcnt(0)
	v_add_f32_e32 v136, v136, v137
	global_atomic_add_f32 v[98:99], v136, off offset:96
.LBB0_511:
	s_or_b64 exec, exec, s[6:7]
	ds_write_b128 v231, v[76:79]
	ds_write_b128 v232, v[72:75]
	ds_read_b128 v[140:143], v233
	v_lshlrev_b32_e32 v144, 16, v164
	ds_write_b128 v231, v[68:71] offset:2048
	ds_write_b128 v232, v[64:67] offset:2048
	s_waitcnt lgkmcnt(5)
	ds_read_b128 v[136:139], v233 offset:2048
	s_waitcnt lgkmcnt(3)
	v_pk_mul_f32 v[140:141], v[132:133], v[140:141]
	s_nop 0
	v_add_f32_e32 v166, v140, v144
	v_and_b32_e32 v140, 0xffff0000, v164
	v_pk_mul_f32 v[142:143], v[134:135], v[142:143]
	v_add_f32_e32 v167, v141, v140
	v_lshlrev_b32_e32 v140, 16, v165
	v_add_f32_e32 v168, v142, v140
	v_and_b32_e32 v140, 0xffff0000, v165
	v_add_f32_e32 v169, v143, v140
	v_mul_f32_e32 v140, v167, v167
	v_fmac_f32_e32 v140, v166, v166
	v_fmac_f32_e32 v140, v168, v168
	v_fmac_f32_e32 v140, v169, v169
	s_nop 1
	v_mov_b32_dpp v141, v140 quad_perm:[1,0,3,2] row_mask:0xf bank_mask:0xf
	v_cvt_pk_bf16_f32 v166, v166, v167
	v_cvt_pk_bf16_f32 v167, v168, v169
	s_waitcnt lgkmcnt(0)
	v_add_f32_e32 v164, v140, v141
	s_nop 1
	v_mov_b32_dpp v165, v164 quad_perm:[2,3,0,1] row_mask:0xf bank_mask:0xf
	ds_read_b128 v[144:147], v230
	ds_read_b128 v[140:143], v234
	global_store_dwordx2 v[188:189], v[166:167], off offset:256
	s_waitcnt lgkmcnt(2)
	v_add_f32_e32 v164, v164, v165
	s_nop 1
	v_mov_b32_dpp v165, v164 row_half_mirror row_mask:0xf bank_mask:0xf
	s_and_saveexec_b64 s[6:7], vcc
	s_cbranch_execz .LBB0_513
	s_waitcnt lgkmcnt(0)
	v_add_f32_e32 v164, v164, v165
	global_atomic_add_f32 v[98:99], v164, off offset:128
; template <int EPI> __device__ __forceinline__ void epi_res(const int tid_e, const GemmArgs& ga, int brow, int bcol, f32x4 (&acc)[2][2][4][2], char* epl) {
;     ...
; #pragma unroll
;   for (int ai = 0; ai < 2; ++ai) {
;     if (EPI != 2) {
; #pragma unroll
;       for (int bj = 0; bj < 2; ++bj)
; #pragma unroll
;         for (int h = 0; h < 2; ++h)
; #pragma unroll
;           for (int i = 0; i < 4; ++i)
;             rb[bj][h][i] = *reinterpret_cast<const u32x2*>(ga.resb + (size_t)(brow + rl0 + ai * 128 + h * 32 + i * 8) * DM + cl0 + bj * 128);
;     }
; #pragma unroll
;     for (int bj = 0; bj < 2; ++bj) {
;       const int col = cl0 + bj * 128;
;       f32x4 scv = {1.f, 1.f, 1.f, 1.f};
;       if (EPI == 3) scv = *reinterpret_cast<const f32x4*>(ga.scale + col);
;       if (EPI == 2) {
; #pragma unroll
;         for (int h = 0; h < 2; ++h)
; #pragma unroll
;           for (int i = 0; i < 4; ++i)
;             rf[h][i] = *reinterpret_cast<const f32x4*>(resf + (size_t)(rl0 + ai * 128 + h * 32 + i * 8) * DM + col);
;       }
; #pragma unroll
;       for (int h = 0; h < 2; ++h) {
; #pragma unroll
;         for (int mm = 0; mm < 2; ++mm) {
;           const int lrow = mm * 16 + fr_e;
; #pragma unroll
;           for (int n = 0; n < 2; ++n)
;             *reinterpret_cast<f32x4*>(sl + lrow * 128 + (((n * 4 + fq_e) ^ ((lrow >> 1) & 7)) * 16)) = acc[ai][bj][h * 2 + mm][n];
;         }
;         f32x4 v[4];
; #pragma unroll
;         for (int i = 0; i < 4; ++i) { const int lrow = i * 8 + rr;
;           v[i] = *reinterpret_cast<const f32x4*>(sl + lrow * 128 + ((rc ^ ((lrow >> 1) & 7)) * 16)); }
; #pragma unroll
;         for (int i = 0; i < 4; ++i) {
;           const int row = brow + rl0 + ai * 128 + h * 32 + i * 8;
;           f32x4 x = v[i];
;           if (EPI == 3) x = x * scv;
;           if (EPI == 2) x = x + rf[h][i];
;           else { const u32x2 r = rb[bj][h][i]; x[0] += bflo(r[0]); x[1] += bfhi(r[0]); x[2] += bflo(r[1]); x[3] += bfhi(r[1]); }
;           if (EPI == 5) *reinterpret_cast<f32x4*>(ga.outf + (size_t)row * DM + col) = x;
;           else {
;             u32x2 w = {cvtpk(x[0], x[1]), cvtpk(x[2], x[3])};
;             *reinterpret_cast<u32x2*>(ga.Cb + (size_t)row * DM + col) = w;
;             float ss = x[0] * x[0] + x[1] * x[1] + x[2] * x[2] + x[3] * x[3];
;             ss += __shfl_xor(ss, 1); ss += __shfl_xor(ss, 2); ss += __shfl_xor(ss, 4);
.LBB0_513:
	s_or_b64 exec, exec, s[6:7]
	s_waitcnt lgkmcnt(1)
	v_pk_mul_f32 v[144:145], v[132:133], v[144:145]
	v_lshlrev_b32_e32 v164, 16, v162
	v_add_f32_e32 v164, v144, v164
	v_and_b32_e32 v144, 0xffff0000, v162
	v_pk_mul_f32 v[146:147], v[134:135], v[146:147]
	v_add_f32_e32 v162, v145, v144
	v_lshlrev_b32_e32 v144, 16, v163
	s_waitcnt lgkmcnt(0)
	v_add_f32_e32 v165, v146, v144
	v_and_b32_e32 v144, 0xffff0000, v163
	v_add_f32_e32 v147, v147, v144
	v_mul_f32_e32 v144, v162, v162
	v_fmac_f32_e32 v144, v164, v164
	v_fmac_f32_e32 v144, v165, v165
	v_fmac_f32_e32 v144, v147, v147
	s_nop 1
	v_mov_b32_dpp v145, v144 quad_perm:[1,0,3,2] row_mask:0xf bank_mask:0xf
	v_cvt_pk_bf16_f32 v146, v164, v162
	v_cvt_pk_bf16_f32 v147, v165, v147
	global_store_dwordx2 v[190:191], v[146:147], off offset:256
	s_waitcnt lgkmcnt(0)
	v_add_f32_e32 v144, v144, v145
	s_nop 1
	v_mov_b32_dpp v145, v144 quad_perm:[2,3,0,1] row_mask:0xf bank_mask:0xf
	s_waitcnt lgkmcnt(0)
	v_add_f32_e32 v144, v144, v145
	s_nop 1
	v_mov_b32_dpp v145, v144 row_half_mirror row_mask:0xf bank_mask:0xf
	s_and_saveexec_b64 s[6:7], vcc
	s_cbranch_execz .LBB0_515
	s_waitcnt lgkmcnt(0)
	v_add_f32_e32 v144, v144, v145
	global_atomic_add_f32 v[98:99], v144, off offset:160
.LBB0_515:
	s_or_b64 exec, exec, s[6:7]
	v_pk_mul_f32 v[136:137], v[132:133], v[136:137]
	v_lshlrev_b32_e32 v144, 16, v160
	v_add_f32_e32 v144, v136, v144
	v_and_b32_e32 v136, 0xffff0000, v160
	v_pk_mul_f32 v[138:139], v[134:135], v[138:139]
	s_waitcnt lgkmcnt(0)
	v_add_f32_e32 v145, v137, v136
	v_lshlrev_b32_e32 v136, 16, v161
	v_add_f32_e32 v146, v138, v136
	v_and_b32_e32 v136, 0xffff0000, v161
	v_add_f32_e32 v139, v139, v136
	v_mul_f32_e32 v136, v145, v145
	v_fmac_f32_e32 v136, v144, v144
	v_fmac_f32_e32 v136, v146, v146
	v_fmac_f32_e32 v136, v139, v139
	s_nop 1
	v_mov_b32_dpp v137, v136 quad_perm:[1,0,3,2] row_mask:0xf bank_mask:0xf
	v_cvt_pk_bf16_f32 v138, v144, v145
	v_cvt_pk_bf16_f32 v139, v146, v139
	global_store_dwordx2 v[178:179], v[138:139], off offset:256
	s_waitcnt lgkmcnt(0)
	v_add_f32_e32 v136, v136, v137
	s_nop 1
	v_mov_b32_dpp v137, v136 quad_perm:[2,3,0,1] row_mask:0xf bank_mask:0xf
	s_waitcnt lgkmcnt(0)
	v_add_f32_e32 v136, v136, v137
	s_nop 1
	v_mov_b32_dpp v137, v136 row_half_mirror row_mask:0xf bank_mask:0xf
	s_and_saveexec_b64 s[6:7], vcc
	s_cbranch_execz .LBB0_517
	s_waitcnt lgkmcnt(0)
	v_add_f32_e32 v136, v136, v137
	global_atomic_add_f32 v[98:99], v136, off offset:192
.LBB0_517:
	s_or_b64 exec, exec, s[6:7]
	v_pk_mul_f32 v[132:133], v[132:133], v[140:141]
	v_lshlrev_b32_e32 v136, 16, v158
	v_add_f32_e32 v136, v132, v136
	v_and_b32_e32 v132, 0xffff0000, v158
	v_pk_mul_f32 v[134:135], v[134:135], v[142:143]
	s_waitcnt lgkmcnt(0)
	v_add_f32_e32 v137, v133, v132
	v_lshlrev_b32_e32 v132, 16, v159
	v_add_f32_e32 v138, v134, v132
	v_and_b32_e32 v132, 0xffff0000, v159
	v_add_f32_e32 v135, v135, v132
	v_mul_f32_e32 v132, v137, v137
	v_fmac_f32_e32 v132, v136, v136
	v_fmac_f32_e32 v132, v138, v138
	v_fmac_f32_e32 v132, v135, v135
	s_nop 1
	v_mov_b32_dpp v133, v132 quad_perm:[1,0,3,2] row_mask:0xf bank_mask:0xf
	v_cvt_pk_bf16_f32 v134, v136, v137
	v_cvt_pk_bf16_f32 v135, v138, v135
	global_store_dwordx2 v[174:175], v[134:135], off offset:256
	s_waitcnt lgkmcnt(0)
	v_add_f32_e32 v132, v132, v133
	s_nop 1
	v_mov_b32_dpp v133, v132 quad_perm:[2,3,0,1] row_mask:0xf bank_mask:0xf
	s_waitcnt lgkmcnt(0)
	v_add_f32_e32 v132, v132, v133
	s_nop 1
	v_mov_b32_dpp v133, v132 row_half_mirror row_mask:0xf bank_mask:0xf
	s_and_saveexec_b64 s[6:7], vcc
	s_cbranch_execz .LBB0_519
	s_waitcnt lgkmcnt(0)
	v_add_f32_e32 v132, v132, v133
	global_atomic_add_f32 v[98:99], v132, off offset:224
.LBB0_519:
	s_or_b64 exec, exec, s[6:7]
	v_lshl_add_u64 v[172:173], v[156:157], 0, s[80:81]
	v_lshl_add_u64 v[136:137], v[154:155], 0, v[172:173]
	s_waitcnt lgkmcnt(0)
	global_load_dwordx4 v[132:135], v[152:153], off
	global_load_dwordx2 v[144:145], v[136:137], off
	s_mov_b64 s[6:7], 0xa0000
	v_lshl_add_u64 v[180:181], v[156:157], 0, s[6:7]
	v_lshl_add_u64 v[174:175], v[156:157], 0, s[82:83]
	v_lshl_add_u64 v[176:177], v[156:157], 0, s[84:85]
	v_lshl_add_u64 v[178:179], v[156:157], 0, s[86:87]
	v_lshl_add_u64 v[182:183], v[156:157], 0, s[88:89]
	v_lshl_add_u64 v[184:185], v[156:157], 0, s[90:91]
	v_lshl_add_u64 v[170:171], v[156:157], 0, s[92:93]
	v_lshl_add_u64 v[138:139], v[154:155], 0, v[174:175]
	v_lshl_add_u64 v[140:141], v[154:155], 0, v[176:177]
	v_lshl_add_u64 v[142:143], v[154:155], 0, v[178:179]
	v_lshl_add_u64 v[146:147], v[154:155], 0, v[180:181]
	v_lshl_add_u64 v[158:159], v[154:155], 0, v[182:183]
	v_lshl_add_u64 v[200:201], v[154:155], 0, v[184:185]
	v_lshl_add_u64 v[154:155], v[154:155], 0, v[170:171]
	global_load_dwordx2 v[198:199], v[138:139], off
	global_load_dwordx2 v[166:167], v[138:139], off offset:256
	global_load_dwordx2 v[168:169], v[136:137], off offset:256
	global_load_dwordx2 v[196:197], v[140:141], off
	global_load_dwordx2 v[194:195], v[142:143], off
	global_load_dwordx2 v[162:163], v[142:143], off offset:256
	global_load_dwordx2 v[164:165], v[140:141], off offset:256
	global_load_dwordx2 v[192:193], v[146:147], off
	global_load_dwordx2 v[190:191], v[158:159], off
	s_nop 0
	global_load_dwordx2 v[158:159], v[158:159], off offset:256
	s_nop 0
	global_load_dwordx2 v[160:161], v[146:147], off offset:256
	global_load_dwordx2 v[188:189], v[200:201], off
	global_load_dwordx2 v[186:187], v[154:155], off
	s_nop 0
	global_load_dwordx2 v[154:155], v[154:155], off offset:256
	s_nop 0
	global_load_dwordx2 v[156:157], v[200:201], off offset:256
	ds_write_b128 v231, v[60:63]
	ds_write_b128 v232, v[56:59]
	ds_read_b128 v[136:139], v233
	ds_write_b128 v231, v[52:55] offset:2048
	ds_write_b128 v232, v[48:51] offset:2048
	ds_read_b128 v[140:143], v233 offset:2048
	v_lshl_add_u64 v[172:173], s[96:97], 0, v[172:173]
	v_lshl_add_u64 v[172:173], v[148:149], 1, v[172:173]
	s_waitcnt vmcnt(16) lgkmcnt(3)
	v_pk_mul_f32 v[136:137], v[132:133], v[136:137]
	s_waitcnt vmcnt(15)
	v_lshlrev_b32_e32 v146, 16, v144
	v_and_b32_e32 v144, 0xffff0000, v144
	v_add_f32_e32 v201, v137, v144
	v_pk_mul_f32 v[138:139], v[134:135], v[138:139]
	v_lshlrev_b32_e32 v147, 16, v145
	v_add_f32_e32 v200, v136, v146
	v_mul_f32_e32 v136, v201, v201
	v_and_b32_e32 v145, 0xffff0000, v145
	v_add_f32_e32 v203, v138, v147
	v_fmac_f32_e32 v136, v200, v200
	v_add_f32_e32 v235, v139, v145
	v_fmac_f32_e32 v136, v203, v203
	v_fmac_f32_e32 v136, v235, v235
	s_nop 1
	v_mov_b32_dpp v137, v136 quad_perm:[1,0,3,2] row_mask:0xf bank_mask:0xf
	v_cvt_pk_bf16_f32 v202, v200, v201
	v_cvt_pk_bf16_f32 v203, v203, v235
	s_waitcnt lgkmcnt(0)
	v_add_f32_e32 v236, v136, v137
	s_nop 1
	v_mov_b32_dpp v237, v236 quad_perm:[2,3,0,1] row_mask:0xf bank_mask:0xf
	ds_read_b128 v[144:147], v230
	ds_read_b128 v[136:139], v234
	global_store_dwordx2 v[172:173], v[202:203], off
	s_waitcnt lgkmcnt(2)
	v_add_f32_e32 v200, v236, v237
	s_nop 1
	v_mov_b32_dpp v201, v200 row_half_mirror row_mask:0xf bank_mask:0xf
	s_and_saveexec_b64 s[6:7], vcc
	s_cbranch_execz .LBB0_521
; __device__ __forceinline__ float bflo(unsigned w) { return __uint_as_float(w << 16); }
; __device__ __forceinline__ float bfhi(unsigned w) { return __uint_as_float(w & 0xffff0000u); }
; template <int EPI> __device__ __forceinline__ void epi_res(const int tid_e, const GemmArgs& ga, int brow, int bcol, f32x4 (&acc)[2][2][4][2], char* epl) {
;     ...
;     for (int bj = 0; bj < 2; ++bj) {
;       const int col = cl0 + bj * 128;
;       f32x4 scv = {1.f, 1.f, 1.f, 1.f};
;       if (EPI == 3) scv = *reinterpret_cast<const f32x4*>(ga.scale + col);
;       if (EPI == 2) {
; #pragma unroll
;         for (int h = 0; h < 2; ++h)
; #pragma unroll
;           for (int i = 0; i < 4; ++i)
;             rf[h][i] = *reinterpret_cast<const f32x4*>(resf + (size_t)(rl0 + ai * 128 + h * 32 + i * 8) * DM + col);
;       }
; #pragma unroll
;       for (int h = 0; h < 2; ++h) {
; #pragma unroll
;         for (int mm = 0; mm < 2; ++mm) {
;           const int lrow = mm * 16 + fr_e;
; #pragma unroll
;           for (int n = 0; n < 2; ++n)
;             *reinterpret_cast<f32x4*>(sl + lrow * 128 + (((n * 4 + fq_e) ^ ((lrow >> 1) & 7)) * 16)) = acc[ai][bj][h * 2 + mm][n];
;         }
;         f32x4 v[4];
; #pragma unroll
;         for (int i = 0; i < 4; ++i) { const int lrow = i * 8 + rr;
;           v[i] = *reinterpret_cast<const f32x4*>(sl + lrow * 128 + ((rc ^ ((lrow >> 1) & 7)) * 16)); }
; #pragma unroll
;         for (int i = 0; i < 4; ++i) {
;           const int row = brow + rl0 + ai * 128 + h * 32 + i * 8;
;           f32x4 x = v[i];
;           if (EPI == 3) x = x * scv;
;           if (EPI == 2) x = x + rf[h][i];
;           else { const u32x2 r = rb[bj][h][i]; x[0] += bflo(r[0]); x[1] += bfhi(r[0]); x[2] += bflo(r[1]); x[3] += bfhi(r[1]); }
;           if (EPI == 5) *reinterpret_cast<f32x4*>(ga.outf + (size_t)row * DM + col) = x;
;           else {
;             u32x2 w = {cvtpk(x[0], x[1]), cvtpk(x[2], x[3])};
;             *reinterpret_cast<u32x2*>(ga.Cb + (size_t)row * DM + col) = w;
;             float ss = x[0] * x[0] + x[1] * x[1] + x[2] * x[2] + x[3] * x[3];
;             ss += __shfl_xor(ss, 1); ss += __shfl_xor(ss, 2); ss += __shfl_xor(ss, 4);
;             if (rc == 0) atomicAdd(ga.rss_out + row, ss);
;           }
;         }
	s_waitcnt lgkmcnt(0)
	v_add_f32_e32 v200, v200, v201
	global_atomic_add_f32 v[98:99], v200, off offset:512
.LBB0_521:
	s_or_b64 exec, exec, s[6:7]
	s_waitcnt lgkmcnt(1)
	v_pk_mul_f32 v[144:145], v[132:133], v[144:145]
	s_waitcnt vmcnt(15)
	v_lshlrev_b32_e32 v200, 16, v198
	v_and_b32_e32 v198, 0xffff0000, v198
	v_pk_mul_f32 v[146:147], v[134:135], v[146:147]
	v_add_f32_e32 v145, v145, v198
	v_lshlrev_b32_e32 v198, 16, v199
	v_add_f32_e32 v198, v146, v198
	v_and_b32_e32 v146, 0xffff0000, v199
	v_add_f32_e32 v144, v144, v200
	v_add_f32_e32 v147, v147, v146
	v_mul_f32_e32 v146, v145, v145
	v_fmac_f32_e32 v146, v144, v144
	v_fmac_f32_e32 v146, v198, v198
	v_fmac_f32_e32 v146, v147, v147
	s_nop 1
	v_mov_b32_dpp v199, v146 quad_perm:[1,0,3,2] row_mask:0xf bank_mask:0xf
	v_lshl_add_u64 v[174:175], s[96:97], 0, v[174:175]
	v_lshl_add_u64 v[174:175], v[148:149], 1, v[174:175]
	v_cvt_pk_bf16_f32 v147, v198, v147
	s_waitcnt lgkmcnt(0)
	v_add_f32_e32 v199, v146, v199
	s_nop 1
	v_mov_b32_dpp v200, v199 quad_perm:[2,3,0,1] row_mask:0xf bank_mask:0xf
	v_cvt_pk_bf16_f32 v146, v144, v145
	global_store_dwordx2 v[174:175], v[146:147], off
	s_waitcnt lgkmcnt(0)
	v_add_f32_e32 v144, v199, v200
	s_nop 1
	v_mov_b32_dpp v145, v144 row_half_mirror row_mask:0xf bank_mask:0xf
	s_and_saveexec_b64 s[6:7], vcc
	s_cbranch_execz .LBB0_523
	s_waitcnt lgkmcnt(0)
	v_add_f32_e32 v144, v144, v145
	global_atomic_add_f32 v[98:99], v144, off offset:544
.LBB0_523:
	s_or_b64 exec, exec, s[6:7]
	v_pk_mul_f32 v[140:141], v[132:133], v[140:141]
	s_waitcnt vmcnt(13)
	v_lshlrev_b32_e32 v144, 16, v196
	v_add_f32_e32 v140, v140, v144
	v_and_b32_e32 v144, 0xffff0000, v196
	v_pk_mul_f32 v[142:143], v[134:135], v[142:143]
	v_add_f32_e32 v141, v141, v144
	v_lshlrev_b32_e32 v144, 16, v197
	v_add_f32_e32 v144, v142, v144
	v_and_b32_e32 v142, 0xffff0000, v197
	v_add_f32_e32 v143, v143, v142
	v_mul_f32_e32 v142, v141, v141
	v_fmac_f32_e32 v142, v140, v140
	v_fmac_f32_e32 v142, v144, v144
	v_fmac_f32_e32 v142, v143, v143
	s_waitcnt lgkmcnt(0)
	s_nop 1
	v_mov_b32_dpp v145, v142 quad_perm:[1,0,3,2] row_mask:0xf bank_mask:0xf
	v_cvt_pk_bf16_f32 v143, v144, v143
	s_waitcnt lgkmcnt(0)
	v_add_f32_e32 v145, v142, v145
	s_nop 1
	v_mov_b32_dpp v146, v145 quad_perm:[2,3,0,1] row_mask:0xf bank_mask:0xf
	v_cvt_pk_bf16_f32 v142, v140, v141
	s_waitcnt lgkmcnt(0)
	v_add_f32_e32 v140, v145, v146
	s_nop 1
	v_mov_b32_dpp v141, v140 row_half_mirror row_mask:0xf bank_mask:0xf
	v_lshl_add_u64 v[144:145], s[96:97], 0, v[176:177]
	v_lshl_add_u64 v[176:177], v[148:149], 1, v[144:145]
	global_store_dwordx2 v[176:177], v[142:143], off
	s_and_saveexec_b64 s[6:7], vcc
	s_cbranch_execz .LBB0_525
	s_waitcnt lgkmcnt(0)
	v_add_f32_e32 v140, v140, v141
	global_atomic_add_f32 v[98:99], v140, off offset:576
.LBB0_525:
	s_or_b64 exec, exec, s[6:7]
	v_pk_mul_f32 v[136:137], v[132:133], v[136:137]
	s_waitcnt vmcnt(13)
	v_lshlrev_b32_e32 v140, 16, v194
	v_add_f32_e32 v136, v136, v140
	v_and_b32_e32 v140, 0xffff0000, v194
	v_pk_mul_f32 v[138:139], v[134:135], v[138:139]
	v_add_f32_e32 v137, v137, v140
	v_lshlrev_b32_e32 v140, 16, v195
	v_add_f32_e32 v140, v138, v140
	v_and_b32_e32 v138, 0xffff0000, v195
	v_add_f32_e32 v139, v139, v138
	v_mul_f32_e32 v138, v137, v137
	v_fmac_f32_e32 v138, v136, v136
	v_fmac_f32_e32 v138, v140, v140
	v_fmac_f32_e32 v138, v139, v139
	s_waitcnt lgkmcnt(0)
	s_nop 1
	v_mov_b32_dpp v141, v138 quad_perm:[1,0,3,2] row_mask:0xf bank_mask:0xf
	v_cvt_pk_bf16_f32 v139, v140, v139
	s_waitcnt lgkmcnt(0)
	v_add_f32_e32 v141, v138, v141
	s_nop 1
	v_mov_b32_dpp v142, v141 quad_perm:[2,3,0,1] row_mask:0xf bank_mask:0xf
	v_cvt_pk_bf16_f32 v138, v136, v137
	s_waitcnt lgkmcnt(0)
	v_add_f32_e32 v136, v141, v142
	s_nop 1
	v_mov_b32_dpp v137, v136 row_half_mirror row_mask:0xf bank_mask:0xf
	v_lshl_add_u64 v[140:141], s[96:97], 0, v[178:179]
	v_lshl_add_u64 v[178:179], v[148:149], 1, v[140:141]
	global_store_dwordx2 v[178:179], v[138:139], off
	s_and_saveexec_b64 s[6:7], vcc
	s_cbranch_execz .LBB0_527
	s_waitcnt lgkmcnt(0)
	v_add_f32_e32 v136, v136, v137
	global_atomic_add_f32 v[98:99], v136, off offset:608
.LBB0_527:
	s_or_b64 exec, exec, s[6:7]
	ds_write_b128 v231, v[44:47]
	ds_write_b128 v232, v[40:43]
	ds_read_b128 v[140:143], v233
	s_waitcnt vmcnt(11)
	v_lshlrev_b32_e32 v144, 16, v192
	ds_write_b128 v231, v[36:39] offset:2048
	ds_write_b128 v232, v[32:35] offset:2048
	s_waitcnt lgkmcnt(5)
	ds_read_b128 v[136:139], v233 offset:2048
	v_lshl_add_u64 v[180:181], s[96:97], 0, v[180:181]
	s_waitcnt lgkmcnt(3)
	v_pk_mul_f32 v[140:141], v[132:133], v[140:141]
	v_pk_mul_f32 v[142:143], v[134:135], v[142:143]
	v_add_f32_e32 v194, v140, v144
	v_and_b32_e32 v140, 0xffff0000, v192
	v_add_f32_e32 v192, v141, v140
	v_lshlrev_b32_e32 v140, 16, v193
	v_add_f32_e32 v195, v142, v140
	v_and_b32_e32 v140, 0xffff0000, v193
	v_add_f32_e32 v196, v143, v140
	v_mul_f32_e32 v140, v192, v192
	v_fmac_f32_e32 v140, v194, v194
	v_fmac_f32_e32 v140, v195, v195
	v_fmac_f32_e32 v140, v196, v196
	s_nop 1
	v_mov_b32_dpp v141, v140 quad_perm:[1,0,3,2] row_mask:0xf bank_mask:0xf
	v_cvt_pk_bf16_f32 v194, v194, v192
	v_lshl_add_u64 v[180:181], v[148:149], 1, v[180:181]
	v_cvt_pk_bf16_f32 v195, v195, v196
	s_waitcnt lgkmcnt(0)
	v_add_f32_e32 v193, v140, v141
	s_nop 1
	v_mov_b32_dpp v197, v193 quad_perm:[2,3,0,1] row_mask:0xf bank_mask:0xf
	ds_read_b128 v[144:147], v230
	ds_read_b128 v[140:143], v234
	global_store_dwordx2 v[180:181], v[194:195], off
	s_waitcnt lgkmcnt(2)
	v_add_f32_e32 v192, v193, v197
	s_nop 1
	v_mov_b32_dpp v193, v192 row_half_mirror row_mask:0xf bank_mask:0xf
	s_and_saveexec_b64 s[6:7], vcc
	s_cbranch_execz .LBB0_529
	s_waitcnt lgkmcnt(0)
	v_add_f32_e32 v192, v192, v193
	global_atomic_add_f32 v[98:99], v192, off offset:640
; __device__ __forceinline__ float bflo(unsigned w) { return __uint_as_float(w << 16); }
; __device__ __forceinline__ float bfhi(unsigned w) { return __uint_as_float(w & 0xffff0000u); }
; template <int EPI> __device__ __forceinline__ void epi_res(const int tid_e, const GemmArgs& ga, int brow, int bcol, f32x4 (&acc)[2][2][4][2], char* epl) {
;     ...
;     for (int bj = 0; bj < 2; ++bj) {
;       const int col = cl0 + bj * 128;
;       f32x4 scv = {1.f, 1.f, 1.f, 1.f};
;       if (EPI == 3) scv = *reinterpret_cast<const f32x4*>(ga.scale + col);
;       if (EPI == 2) {
; #pragma unroll
;         for (int h = 0; h < 2; ++h)
; #pragma unroll
;           for (int i = 0; i < 4; ++i)
;             rf[h][i] = *reinterpret_cast<const f32x4*>(resf + (size_t)(rl0 + ai * 128 + h * 32 + i * 8) * DM + col);
;       }
; #pragma unroll
;       for (int h = 0; h < 2; ++h) {
; #pragma unroll
;         for (int mm = 0; mm < 2; ++mm) {
;           const int lrow = mm * 16 + fr_e;
; #pragma unroll
;           for (int n = 0; n < 2; ++n)
;             *reinterpret_cast<f32x4*>(sl + lrow * 128 + (((n * 4 + fq_e) ^ ((lrow >> 1) & 7)) * 16)) = acc[ai][bj][h * 2 + mm][n];
;         }
;         f32x4 v[4];
; #pragma unroll
;         for (int i = 0; i < 4; ++i) { const int lrow = i * 8 + rr;
;           v[i] = *reinterpret_cast<const f32x4*>(sl + lrow * 128 + ((rc ^ ((lrow >> 1) & 7)) * 16)); }
; #pragma unroll
;         for (int i = 0; i < 4; ++i) {
;           const int row = brow + rl0 + ai * 128 + h * 32 + i * 8;
;           f32x4 x = v[i];
;           if (EPI == 3) x = x * scv;
;           if (EPI == 2) x = x + rf[h][i];
;           else { const u32x2 r = rb[bj][h][i]; x[0] += bflo(r[0]); x[1] += bfhi(r[0]); x[2] += bflo(r[1]); x[3] += bfhi(r[1]); }
;           if (EPI == 5) *reinterpret_cast<f32x4*>(ga.outf + (size_t)row * DM + col) = x;
;           else {
;             u32x2 w = {cvtpk(x[0], x[1]), cvtpk(x[2], x[3])};
;             *reinterpret_cast<u32x2*>(ga.Cb + (size_t)row * DM + col) = w;
;             float ss = x[0] * x[0] + x[1] * x[1] + x[2] * x[2] + x[3] * x[3];
;             ss += __shfl_xor(ss, 1); ss += __shfl_xor(ss, 2); ss += __shfl_xor(ss, 4);
;             if (rc == 0) atomicAdd(ga.rss_out + row, ss);
;           }
;         }
.LBB0_529:
	s_or_b64 exec, exec, s[6:7]
	s_waitcnt lgkmcnt(1)
	v_pk_mul_f32 v[144:145], v[132:133], v[144:145]
	s_waitcnt vmcnt(11)
	v_lshlrev_b32_e32 v192, 16, v190
	v_and_b32_e32 v190, 0xffff0000, v190
	v_pk_mul_f32 v[146:147], v[134:135], v[146:147]
	v_add_f32_e32 v145, v145, v190
	v_lshlrev_b32_e32 v190, 16, v191
	v_add_f32_e32 v190, v146, v190
	v_and_b32_e32 v146, 0xffff0000, v191
	v_add_f32_e32 v144, v144, v192
	v_add_f32_e32 v147, v147, v146
	v_mul_f32_e32 v146, v145, v145
	v_fmac_f32_e32 v146, v144, v144
	v_fmac_f32_e32 v146, v190, v190
	v_fmac_f32_e32 v146, v147, v147
	s_nop 1
	v_mov_b32_dpp v191, v146 quad_perm:[1,0,3,2] row_mask:0xf bank_mask:0xf
	v_lshl_add_u64 v[182:183], s[96:97], 0, v[182:183]
	v_lshl_add_u64 v[182:183], v[148:149], 1, v[182:183]
	v_cvt_pk_bf16_f32 v147, v190, v147
	s_waitcnt lgkmcnt(0)
	v_add_f32_e32 v191, v146, v191
	s_nop 1
	v_mov_b32_dpp v192, v191 quad_perm:[2,3,0,1] row_mask:0xf bank_mask:0xf
	v_cvt_pk_bf16_f32 v146, v144, v145
	global_store_dwordx2 v[182:183], v[146:147], off
	s_waitcnt lgkmcnt(0)
	v_add_f32_e32 v144, v191, v192
	s_nop 1
	v_mov_b32_dpp v145, v144 row_half_mirror row_mask:0xf bank_mask:0xf
	s_and_saveexec_b64 s[6:7], vcc
	s_cbranch_execz .LBB0_531
	s_waitcnt lgkmcnt(0)
	v_add_f32_e32 v144, v144, v145
	global_atomic_add_f32 v[98:99], v144, off offset:672
.LBB0_531:
	s_or_b64 exec, exec, s[6:7]
	v_pk_mul_f32 v[136:137], v[132:133], v[136:137]
	s_waitcnt vmcnt(9)
	v_lshlrev_b32_e32 v144, 16, v188
	v_add_f32_e32 v136, v136, v144
	v_and_b32_e32 v144, 0xffff0000, v188
	v_pk_mul_f32 v[138:139], v[134:135], v[138:139]
	v_add_f32_e32 v137, v137, v144
	v_lshlrev_b32_e32 v144, 16, v189
	v_add_f32_e32 v144, v138, v144
	v_and_b32_e32 v138, 0xffff0000, v189
	v_add_f32_e32 v139, v139, v138
	v_mul_f32_e32 v138, v137, v137
	v_fmac_f32_e32 v138, v136, v136
	v_fmac_f32_e32 v138, v144, v144
	v_fmac_f32_e32 v138, v139, v139
	s_waitcnt lgkmcnt(0)
	s_nop 1
	v_mov_b32_dpp v145, v138 quad_perm:[1,0,3,2] row_mask:0xf bank_mask:0xf
	v_cvt_pk_bf16_f32 v139, v144, v139
	s_waitcnt lgkmcnt(0)
	v_add_f32_e32 v145, v138, v145
	s_nop 1
	v_mov_b32_dpp v146, v145 quad_perm:[2,3,0,1] row_mask:0xf bank_mask:0xf
	v_cvt_pk_bf16_f32 v138, v136, v137
	s_waitcnt lgkmcnt(0)
	v_add_f32_e32 v136, v145, v146
	s_nop 1
	v_mov_b32_dpp v137, v136 row_half_mirror row_mask:0xf bank_mask:0xf
	v_lshl_add_u64 v[144:145], s[96:97], 0, v[184:185]
	v_lshl_add_u64 v[184:185], v[148:149], 1, v[144:145]
	global_store_dwordx2 v[184:185], v[138:139], off
	s_and_saveexec_b64 s[6:7], vcc
	s_cbranch_execz .LBB0_533
	s_waitcnt lgkmcnt(0)
	v_add_f32_e32 v136, v136, v137
	global_atomic_add_f32 v[98:99], v136, off offset:704
.LBB0_533:
	s_or_b64 exec, exec, s[6:7]
	v_pk_mul_f32 v[132:133], v[132:133], v[140:141]
	s_waitcnt vmcnt(9)
	v_lshlrev_b32_e32 v136, 16, v186
	v_add_f32_e32 v132, v132, v136
	v_and_b32_e32 v136, 0xffff0000, v186
	v_pk_mul_f32 v[134:135], v[134:135], v[142:143]
	v_add_f32_e32 v133, v133, v136
	v_lshlrev_b32_e32 v136, 16, v187
	v_add_f32_e32 v136, v134, v136
	v_and_b32_e32 v134, 0xffff0000, v187
	v_add_f32_e32 v135, v135, v134
	v_mul_f32_e32 v134, v133, v133
	v_fmac_f32_e32 v134, v132, v132
	v_fmac_f32_e32 v134, v136, v136
	v_fmac_f32_e32 v134, v135, v135
	s_waitcnt lgkmcnt(0)
	s_nop 1
	v_mov_b32_dpp v137, v134 quad_perm:[1,0,3,2] row_mask:0xf bank_mask:0xf
	v_cvt_pk_bf16_f32 v135, v136, v135
	s_waitcnt lgkmcnt(0)
	v_add_f32_e32 v137, v134, v137
	s_nop 1
	v_mov_b32_dpp v138, v137 quad_perm:[2,3,0,1] row_mask:0xf bank_mask:0xf
	v_cvt_pk_bf16_f32 v134, v132, v133
	s_waitcnt lgkmcnt(0)
	v_add_f32_e32 v132, v137, v138
	s_nop 1
	v_mov_b32_dpp v133, v132 row_half_mirror row_mask:0xf bank_mask:0xf
	v_lshl_add_u64 v[136:137], s[96:97], 0, v[170:171]
	v_lshl_add_u64 v[148:149], v[148:149], 1, v[136:137]
	global_store_dwordx2 v[148:149], v[134:135], off
	s_and_saveexec_b64 s[6:7], vcc
	s_cbranch_execz .LBB0_535
	s_waitcnt lgkmcnt(0)
	v_add_f32_e32 v132, v132, v133
	global_atomic_add_f32 v[98:99], v132, off offset:736
.LBB0_535:
	s_or_b64 exec, exec, s[6:7]
	s_waitcnt lgkmcnt(0)
	global_load_dwordx4 v[132:135], v[152:153], off offset:512
	ds_write_b128 v231, v[28:31]
	ds_write_b128 v232, v[24:27]
	ds_write_b128 v231, v[20:23] offset:2048
	ds_write_b128 v232, v[16:19] offset:2048
	ds_read_b128 v[136:139], v233
	ds_read_b128 v[140:143], v233 offset:2048
	v_and_b32_e32 v145, 0xffff0000, v168
	v_lshlrev_b32_e32 v144, 16, v168
	v_lshlrev_b32_e32 v146, 16, v169
	v_and_b32_e32 v147, 0xffff0000, v169
	s_waitcnt vmcnt(0) lgkmcnt(1)
	v_pk_mul_f32 v[136:137], v[132:133], v[136:137]
	s_nop 0
	v_add_f32_e32 v169, v137, v145
	v_pk_mul_f32 v[138:139], v[134:135], v[138:139]
	v_add_f32_e32 v168, v136, v144
	v_mul_f32_e32 v136, v169, v169
	v_add_f32_e32 v170, v138, v146
	v_fmac_f32_e32 v136, v168, v168
	v_add_f32_e32 v171, v139, v147
	v_fmac_f32_e32 v136, v170, v170
	v_fmac_f32_e32 v136, v171, v171
	s_nop 1
	v_mov_b32_dpp v137, v136 quad_perm:[1,0,3,2] row_mask:0xf bank_mask:0xf
	v_cvt_pk_bf16_f32 v168, v168, v169
	v_cvt_pk_bf16_f32 v169, v170, v171
	s_waitcnt lgkmcnt(0)
	v_add_f32_e32 v152, v136, v137
	s_nop 1
	v_mov_b32_dpp v153, v152 quad_perm:[2,3,0,1] row_mask:0xf bank_mask:0xf
	ds_read_b128 v[144:147], v230
	ds_read_b128 v[136:139], v234
	global_store_dwordx2 v[172:173], v[168:169], off offset:256
	s_waitcnt lgkmcnt(2)
	v_add_f32_e32 v152, v152, v153
	s_nop 1
	v_mov_b32_dpp v153, v152 row_half_mirror row_mask:0xf bank_mask:0xf
	s_and_saveexec_b64 s[6:7], vcc
	s_cbranch_execz .LBB0_537
	s_waitcnt lgkmcnt(0)
	v_add_f32_e32 v152, v152, v153
	global_atomic_add_f32 v[98:99], v152, off offset:512
; __device__ __forceinline__ float bflo(unsigned w) { return __uint_as_float(w << 16); }
; __device__ __forceinline__ float bfhi(unsigned w) { return __uint_as_float(w & 0xffff0000u); }
; template <int EPI> __device__ __forceinline__ void epi_res(const int tid_e, const GemmArgs& ga, int brow, int bcol, f32x4 (&acc)[2][2][4][2], char* epl) {
;     ...
;     for (int bj = 0; bj < 2; ++bj) {
;       const int col = cl0 + bj * 128;
;       f32x4 scv = {1.f, 1.f, 1.f, 1.f};
;       if (EPI == 3) scv = *reinterpret_cast<const f32x4*>(ga.scale + col);
;       if (EPI == 2) {
; #pragma unroll
;         for (int h = 0; h < 2; ++h)
; #pragma unroll
;           for (int i = 0; i < 4; ++i)
;             rf[h][i] = *reinterpret_cast<const f32x4*>(resf + (size_t)(rl0 + ai * 128 + h * 32 + i * 8) * DM + col);
;       }
; #pragma unroll
;       for (int h = 0; h < 2; ++h) {
; #pragma unroll
;         for (int mm = 0; mm < 2; ++mm) {
;           const int lrow = mm * 16 + fr_e;
; #pragma unroll
;           for (int n = 0; n < 2; ++n)
;             *reinterpret_cast<f32x4*>(sl + lrow * 128 + (((n * 4 + fq_e) ^ ((lrow >> 1) & 7)) * 16)) = acc[ai][bj][h * 2 + mm][n];
;         }
;         f32x4 v[4];
; #pragma unroll
;         for (int i = 0; i < 4; ++i) { const int lrow = i * 8 + rr;
;           v[i] = *reinterpret_cast<const f32x4*>(sl + lrow * 128 + ((rc ^ ((lrow >> 1) & 7)) * 16)); }
; #pragma unroll
;         for (int i = 0; i < 4; ++i) {
;           const int row = brow + rl0 + ai * 128 + h * 32 + i * 8;
;           f32x4 x = v[i];
;           if (EPI == 3) x = x * scv;
;           if (EPI == 2) x = x + rf[h][i];
;           else { const u32x2 r = rb[bj][h][i]; x[0] += bflo(r[0]); x[1] += bfhi(r[0]); x[2] += bflo(r[1]); x[3] += bfhi(r[1]); }
;           if (EPI == 5) *reinterpret_cast<f32x4*>(ga.outf + (size_t)row * DM + col) = x;
;           else {
;             u32x2 w = {cvtpk(x[0], x[1]), cvtpk(x[2], x[3])};
;             *reinterpret_cast<u32x2*>(ga.Cb + (size_t)row * DM + col) = w;
;             float ss = x[0] * x[0] + x[1] * x[1] + x[2] * x[2] + x[3] * x[3];
;             ss += __shfl_xor(ss, 1); ss += __shfl_xor(ss, 2); ss += __shfl_xor(ss, 4);
;             if (rc == 0) atomicAdd(ga.rss_out + row, ss);
;           }
;         }
.LBB0_537:
	s_or_b64 exec, exec, s[6:7]
	s_waitcnt lgkmcnt(1)
	v_pk_mul_f32 v[144:145], v[132:133], v[144:145]
	v_lshlrev_b32_e32 v152, 16, v166
	v_add_f32_e32 v152, v144, v152
	v_and_b32_e32 v144, 0xffff0000, v166
	v_pk_mul_f32 v[146:147], v[134:135], v[146:147]
	s_waitcnt lgkmcnt(0)
	v_add_f32_e32 v153, v145, v144
	v_lshlrev_b32_e32 v144, 16, v167
	v_add_f32_e32 v166, v146, v144
	v_and_b32_e32 v144, 0xffff0000, v167
	v_add_f32_e32 v147, v147, v144
	v_mul_f32_e32 v144, v153, v153
	v_fmac_f32_e32 v144, v152, v152
	v_fmac_f32_e32 v144, v166, v166
	v_fmac_f32_e32 v144, v147, v147
	s_nop 1
	v_mov_b32_dpp v145, v144 quad_perm:[1,0,3,2] row_mask:0xf bank_mask:0xf
	v_cvt_pk_bf16_f32 v146, v152, v153
	v_cvt_pk_bf16_f32 v147, v166, v147
	global_store_dwordx2 v[174:175], v[146:147], off offset:256
	s_waitcnt lgkmcnt(0)
	v_add_f32_e32 v144, v144, v145
	s_nop 1
	v_mov_b32_dpp v145, v144 quad_perm:[2,3,0,1] row_mask:0xf bank_mask:0xf
	s_waitcnt lgkmcnt(0)
	v_add_f32_e32 v144, v144, v145
	s_nop 1
	v_mov_b32_dpp v145, v144 row_half_mirror row_mask:0xf bank_mask:0xf
	s_and_saveexec_b64 s[6:7], vcc
	s_cbranch_execz .LBB0_539
	s_waitcnt lgkmcnt(0)
	v_add_f32_e32 v144, v144, v145
	global_atomic_add_f32 v[98:99], v144, off offset:544
.LBB0_539:
	s_or_b64 exec, exec, s[6:7]
	v_pk_mul_f32 v[140:141], v[132:133], v[140:141]
	v_lshlrev_b32_e32 v144, 16, v164
	v_add_f32_e32 v144, v140, v144
	v_and_b32_e32 v140, 0xffff0000, v164
	v_pk_mul_f32 v[142:143], v[134:135], v[142:143]
	s_waitcnt lgkmcnt(0)
	v_add_f32_e32 v145, v141, v140
	v_lshlrev_b32_e32 v140, 16, v165
	v_add_f32_e32 v146, v142, v140
	v_and_b32_e32 v140, 0xffff0000, v165
	v_add_f32_e32 v143, v143, v140
	v_mul_f32_e32 v140, v145, v145
	v_fmac_f32_e32 v140, v144, v144
	v_fmac_f32_e32 v140, v146, v146
	v_fmac_f32_e32 v140, v143, v143
	s_nop 1
	v_mov_b32_dpp v141, v140 quad_perm:[1,0,3,2] row_mask:0xf bank_mask:0xf
	v_cvt_pk_bf16_f32 v142, v144, v145
	v_cvt_pk_bf16_f32 v143, v146, v143
	global_store_dwordx2 v[176:177], v[142:143], off offset:256
	s_waitcnt lgkmcnt(0)
	v_add_f32_e32 v140, v140, v141
	s_nop 1
	v_mov_b32_dpp v141, v140 quad_perm:[2,3,0,1] row_mask:0xf bank_mask:0xf
	s_waitcnt lgkmcnt(0)
	v_add_f32_e32 v140, v140, v141
	s_nop 1
	v_mov_b32_dpp v141, v140 row_half_mirror row_mask:0xf bank_mask:0xf
	s_and_saveexec_b64 s[6:7], vcc
	s_cbranch_execz .LBB0_541
	s_waitcnt lgkmcnt(0)
	v_add_f32_e32 v140, v140, v141
	global_atomic_add_f32 v[98:99], v140, off offset:576
.LBB0_541:
	s_or_b64 exec, exec, s[6:7]
	v_pk_mul_f32 v[136:137], v[132:133], v[136:137]
	v_lshlrev_b32_e32 v140, 16, v162
	v_add_f32_e32 v140, v136, v140
	v_and_b32_e32 v136, 0xffff0000, v162
	v_pk_mul_f32 v[138:139], v[134:135], v[138:139]
	s_waitcnt lgkmcnt(0)
	v_add_f32_e32 v141, v137, v136
	v_lshlrev_b32_e32 v136, 16, v163
	v_add_f32_e32 v142, v138, v136
	v_and_b32_e32 v136, 0xffff0000, v163
	v_add_f32_e32 v139, v139, v136
	v_mul_f32_e32 v136, v141, v141
	v_fmac_f32_e32 v136, v140, v140
	v_fmac_f32_e32 v136, v142, v142
	v_fmac_f32_e32 v136, v139, v139
	s_nop 1
	v_mov_b32_dpp v137, v136 quad_perm:[1,0,3,2] row_mask:0xf bank_mask:0xf
	v_cvt_pk_bf16_f32 v138, v140, v141
	v_cvt_pk_bf16_f32 v139, v142, v139
	global_store_dwordx2 v[178:179], v[138:139], off offset:256
	s_waitcnt lgkmcnt(0)
	v_add_f32_e32 v136, v136, v137
	s_nop 1
	v_mov_b32_dpp v137, v136 quad_perm:[2,3,0,1] row_mask:0xf bank_mask:0xf
	s_waitcnt lgkmcnt(0)
	v_add_f32_e32 v136, v136, v137
	s_nop 1
	v_mov_b32_dpp v137, v136 row_half_mirror row_mask:0xf bank_mask:0xf
	s_and_saveexec_b64 s[6:7], vcc
	s_cbranch_execz .LBB0_543
	s_waitcnt lgkmcnt(0)
	v_add_f32_e32 v136, v136, v137
	global_atomic_add_f32 v[98:99], v136, off offset:608
; __device__ __forceinline__ float bflo(unsigned w) { return __uint_as_float(w << 16); }
; __device__ __forceinline__ float bfhi(unsigned w) { return __uint_as_float(w & 0xffff0000u); }
; template <int EPI> __device__ __forceinline__ void epi_res(const int tid_e, const GemmArgs& ga, int brow, int bcol, f32x4 (&acc)[2][2][4][2], char* epl) {
;     ...
;     for (int bj = 0; bj < 2; ++bj) {
;       const int col = cl0 + bj * 128;
;       f32x4 scv = {1.f, 1.f, 1.f, 1.f};
;       if (EPI == 3) scv = *reinterpret_cast<const f32x4*>(ga.scale + col);
;       if (EPI == 2) {
; #pragma unroll
;         for (int h = 0; h < 2; ++h)
; #pragma unroll
;           for (int i = 0; i < 4; ++i)
;             rf[h][i] = *reinterpret_cast<const f32x4*>(resf + (size_t)(rl0 + ai * 128 + h * 32 + i * 8) * DM + col);
;       }
; #pragma unroll
;       for (int h = 0; h < 2; ++h) {
; #pragma unroll
;         for (int mm = 0; mm < 2; ++mm) {
;           const int lrow = mm * 16 + fr_e;
; #pragma unroll
;           for (int n = 0; n < 2; ++n)
;             *reinterpret_cast<f32x4*>(sl + lrow * 128 + (((n * 4 + fq_e) ^ ((lrow >> 1) & 7)) * 16)) = acc[ai][bj][h * 2 + mm][n];
;         }
;         f32x4 v[4];
; #pragma unroll
;         for (int i = 0; i < 4; ++i) { const int lrow = i * 8 + rr;
;           v[i] = *reinterpret_cast<const f32x4*>(sl + lrow * 128 + ((rc ^ ((lrow >> 1) & 7)) * 16)); }
; #pragma unroll
;         for (int i = 0; i < 4; ++i) {
;           const int row = brow + rl0 + ai * 128 + h * 32 + i * 8;
;           f32x4 x = v[i];
;           if (EPI == 3) x = x * scv;
;           if (EPI == 2) x = x + rf[h][i];
;           else { const u32x2 r = rb[bj][h][i]; x[0] += bflo(r[0]); x[1] += bfhi(r[0]); x[2] += bflo(r[1]); x[3] += bfhi(r[1]); }
;           if (EPI == 5) *reinterpret_cast<f32x4*>(ga.outf + (size_t)row * DM + col) = x;
;           else {
;             u32x2 w = {cvtpk(x[0], x[1]), cvtpk(x[2], x[3])};
;             *reinterpret_cast<u32x2*>(ga.Cb + (size_t)row * DM + col) = w;
;             float ss = x[0] * x[0] + x[1] * x[1] + x[2] * x[2] + x[3] * x[3];
;             ss += __shfl_xor(ss, 1); ss += __shfl_xor(ss, 2); ss += __shfl_xor(ss, 4);
;             if (rc == 0) atomicAdd(ga.rss_out + row, ss);
;           }
;         }
.LBB0_543:
	s_or_b64 exec, exec, s[6:7]
	ds_write_b128 v231, v[12:15]
	ds_write_b128 v232, v[8:11]
	ds_read_b128 v[140:143], v233
	v_lshlrev_b32_e32 v144, 16, v160
	ds_write_b128 v231, v[4:7] offset:2048
	ds_write_b128 v232, v[0:3] offset:2048
	s_waitcnt lgkmcnt(5)
	ds_read_b128 v[136:139], v233 offset:2048
	s_waitcnt lgkmcnt(3)
	v_pk_mul_f32 v[140:141], v[132:133], v[140:141]
	s_nop 0
	v_add_f32_e32 v162, v140, v144
	v_and_b32_e32 v140, 0xffff0000, v160
	v_pk_mul_f32 v[142:143], v[134:135], v[142:143]
	v_add_f32_e32 v160, v141, v140
	v_lshlrev_b32_e32 v140, 16, v161
	v_add_f32_e32 v163, v142, v140
	v_and_b32_e32 v140, 0xffff0000, v161
	v_add_f32_e32 v161, v143, v140
	v_mul_f32_e32 v140, v160, v160
	v_fmac_f32_e32 v140, v162, v162
	v_fmac_f32_e32 v140, v163, v163
	v_fmac_f32_e32 v140, v161, v161
	s_nop 1
	v_mov_b32_dpp v141, v140 quad_perm:[1,0,3,2] row_mask:0xf bank_mask:0xf
	v_cvt_pk_bf16_f32 v160, v162, v160
	v_cvt_pk_bf16_f32 v161, v163, v161
	s_waitcnt lgkmcnt(0)
	v_add_f32_e32 v152, v140, v141
	s_nop 1
	v_mov_b32_dpp v153, v152 quad_perm:[2,3,0,1] row_mask:0xf bank_mask:0xf
	ds_read_b128 v[144:147], v230
	ds_read_b128 v[140:143], v234
	global_store_dwordx2 v[180:181], v[160:161], off offset:256
	s_waitcnt lgkmcnt(2)
	v_add_f32_e32 v152, v152, v153
	s_nop 1
	v_mov_b32_dpp v153, v152 row_half_mirror row_mask:0xf bank_mask:0xf
	s_and_saveexec_b64 s[6:7], vcc
	s_cbranch_execz .LBB0_545
	s_waitcnt lgkmcnt(0)
	v_add_f32_e32 v152, v152, v153
	global_atomic_add_f32 v[98:99], v152, off offset:640
.LBB0_545:
	s_or_b64 exec, exec, s[6:7]
	s_waitcnt lgkmcnt(1)
	v_pk_mul_f32 v[144:145], v[132:133], v[144:145]
	v_lshlrev_b32_e32 v152, 16, v158
	v_add_f32_e32 v152, v144, v152
	v_and_b32_e32 v144, 0xffff0000, v158
	v_pk_mul_f32 v[146:147], v[134:135], v[146:147]
	s_waitcnt lgkmcnt(0)
	v_add_f32_e32 v153, v145, v144
	v_lshlrev_b32_e32 v144, 16, v159
	v_add_f32_e32 v158, v146, v144
	v_and_b32_e32 v144, 0xffff0000, v159
	v_add_f32_e32 v147, v147, v144
	v_mul_f32_e32 v144, v153, v153
	v_fmac_f32_e32 v144, v152, v152
	v_fmac_f32_e32 v144, v158, v158
	v_fmac_f32_e32 v144, v147, v147
	s_nop 1
	v_mov_b32_dpp v145, v144 quad_perm:[1,0,3,2] row_mask:0xf bank_mask:0xf
	v_cvt_pk_bf16_f32 v146, v152, v153
	v_cvt_pk_bf16_f32 v147, v158, v147
	global_store_dwordx2 v[182:183], v[146:147], off offset:256
	s_waitcnt lgkmcnt(0)
	v_add_f32_e32 v144, v144, v145
	s_nop 1
	v_mov_b32_dpp v145, v144 quad_perm:[2,3,0,1] row_mask:0xf bank_mask:0xf
	s_waitcnt lgkmcnt(0)
	v_add_f32_e32 v144, v144, v145
	s_nop 1
	v_mov_b32_dpp v145, v144 row_half_mirror row_mask:0xf bank_mask:0xf
	s_and_saveexec_b64 s[6:7], vcc
	s_cbranch_execz .LBB0_547
	s_waitcnt lgkmcnt(0)
	v_add_f32_e32 v144, v144, v145
	global_atomic_add_f32 v[98:99], v144, off offset:672
.LBB0_547:
	s_or_b64 exec, exec, s[6:7]
	v_pk_mul_f32 v[136:137], v[132:133], v[136:137]
	v_lshlrev_b32_e32 v144, 16, v156
	v_add_f32_e32 v144, v136, v144
	v_and_b32_e32 v136, 0xffff0000, v156
	v_pk_mul_f32 v[138:139], v[134:135], v[138:139]
	s_waitcnt lgkmcnt(0)
	v_add_f32_e32 v145, v137, v136
	v_lshlrev_b32_e32 v136, 16, v157
	v_add_f32_e32 v146, v138, v136
	v_and_b32_e32 v136, 0xffff0000, v157
	v_add_f32_e32 v139, v139, v136
	v_mul_f32_e32 v136, v145, v145
	v_fmac_f32_e32 v136, v144, v144
	v_fmac_f32_e32 v136, v146, v146
	v_fmac_f32_e32 v136, v139, v139
	s_nop 1
	v_mov_b32_dpp v137, v136 quad_perm:[1,0,3,2] row_mask:0xf bank_mask:0xf
	v_cvt_pk_bf16_f32 v138, v144, v145
	v_cvt_pk_bf16_f32 v139, v146, v139
	global_store_dwordx2 v[184:185], v[138:139], off offset:256
	s_waitcnt lgkmcnt(0)
	v_add_f32_e32 v136, v136, v137
	s_nop 1
	v_mov_b32_dpp v137, v136 quad_perm:[2,3,0,1] row_mask:0xf bank_mask:0xf
	s_waitcnt lgkmcnt(0)
	v_add_f32_e32 v136, v136, v137
	s_nop 1
	v_mov_b32_dpp v137, v136 row_half_mirror row_mask:0xf bank_mask:0xf
	s_and_saveexec_b64 s[6:7], vcc
	s_cbranch_execz .LBB0_549
	s_waitcnt lgkmcnt(0)
	v_add_f32_e32 v136, v136, v137
	global_atomic_add_f32 v[98:99], v136, off offset:704
.LBB0_549:
	s_or_b64 exec, exec, s[6:7]
	v_pk_mul_f32 v[132:133], v[132:133], v[140:141]
	v_lshlrev_b32_e32 v136, 16, v154
	v_add_f32_e32 v136, v132, v136
	v_and_b32_e32 v132, 0xffff0000, v154
	v_pk_mul_f32 v[134:135], v[134:135], v[142:143]
	v_add_f32_e32 v133, v133, v132
	v_lshlrev_b32_e32 v132, 16, v155
	s_waitcnt lgkmcnt(0)
	v_add_f32_e32 v137, v134, v132
	v_and_b32_e32 v132, 0xffff0000, v155
	v_add_f32_e32 v135, v135, v132
	v_mul_f32_e32 v132, v133, v133
	v_fmac_f32_e32 v132, v136, v136
	v_fmac_f32_e32 v132, v137, v137
	v_fmac_f32_e32 v132, v135, v135
	s_nop 1
	v_mov_b32_dpp v96, v132 quad_perm:[1,0,3,2] row_mask:0xf bank_mask:0xf
	v_cvt_pk_bf16_f32 v134, v136, v133
	v_cvt_pk_bf16_f32 v135, v137, v135
	global_store_dwordx2 v[148:149], v[134:135], off offset:256
	s_waitcnt lgkmcnt(0)
	v_add_f32_e32 v96, v132, v96
	s_nop 1
	v_mov_b32_dpp v132, v96 quad_perm:[2,3,0,1] row_mask:0xf bank_mask:0xf
	s_waitcnt lgkmcnt(0)
	v_add_f32_e32 v96, v96, v132
	s_nop 1
	v_mov_b32_dpp v132, v96 row_half_mirror row_mask:0xf bank_mask:0xf
	s_and_saveexec_b64 s[6:7], vcc
	s_cbranch_execz .LBB0_551
	s_waitcnt lgkmcnt(0)
	v_add_f32_e32 v96, v96, v132
	global_atomic_add_f32 v[98:99], v96, off offset:736
